# loop-edge edit form 2: K-loop counter/pointer/exit-test SALU interleaved into the last phase's MFMA run (only the branch follows the loop-back barrier), six GEMM loops, v93 base
# baseline (speedup 1.0000x reference)
; #define PG8_STAGE(bufoff, gbase, voff) do { _Pragma("unroll") for (int _i = 0; _i < 2; ++_i) \
;         __builtin_amdgcn_global_load_lds((const unsigned*)((const char*)(gbase) + (voff)[_i]), (LAS unsigned*)(lds + (bufoff) + ldsw + _i * 8192), 16, 0, 0); } while (0)
; #define PG8_LDA(dst, b, h) do { _Pragma("unroll") for (int m = 0; m < 4; ++m) _Pragma("unroll") for (int k = 0; k < 2; ++k) dst[m][k] = *(const LAS bf16x8*)(lds + PG8_SA(b, h) + aoff + m * 2048 + k * 1024); } while (0)
; #define PG8_LDB(dst, b, h) do { _Pragma("unroll") for (int n = 0; n < 2; ++n) _Pragma("unroll") for (int k = 0; k < 2; ++k) dst[n][k] = *(const LAS bf16x8*)(lds + PG8_SB(b, h) + boff + n * 2048 + k * 1024); } while (0)
; #define PG8_MMA(ai, bj, At, Bt) do { __builtin_amdgcn_s_setprio(1); _Pragma("unroll") for (int m = 0; m < 4; ++m) _Pragma("unroll") for (int n = 0; n < 2; ++n) _Pragma("unroll") for (int k = 0; k < 2; ++k) \
;         acc[ai][bj][m][n] = __builtin_amdgcn_mfma_f32_16x16x32_bf16(Bt[n][k], At[m][k], acc[ai][bj][m][n], 0, 0, 0); __builtin_amdgcn_s_setprio(0); } while (0)
; #define PG8_WAIT_V(n) asm volatile("s_waitcnt vmcnt(" #n ")" ::: "memory")
; #define PG8_WAIT_L(n) asm volatile("s_waitcnt lgkmcnt(" #n ")" ::: "memory")
; #define PG8_BAR __builtin_amdgcn_s_barrier()
; #define PG8_SCHED __builtin_amdgcn_sched_barrier(0)
; template <class Epi, class Sched>
; __device__ __forceinline__ void gemm_phase(LAS unsigned char* lds, const Gemm g, const Sched& S, const Epi& E) {
;     ...
;         for (int t = 0; t < nt; t += 2) {
;             const bool last = (t == nt - 2);
;             const char* a1 = cA + (size_t)(t + 1) * kstep;
;             const char* a2 = last ? nA : cA + (size_t)(t + 2) * kstep; const char* b2 = last ? nB : cB + (size_t)(t + 2) * kstep;
;             const char* a3 = a2 + kstep; const char* b3 = b2 + kstep;
;             PG8_LDB(B0, 0, 0); PG8_LDB(B1, 0, 1); PG8_SCHED; PG8_LDA(At, 0, 0); PG8_STAGE(PG8_SA(1, 1), a1 + hstepA, voffA);
;             PG8_WAIT_V(8); PG8_WAIT_L(0); PG8_BAR; PG8_MMA(0, 0, At, B0); PG8_MMA(0, 1, At, B1); PG8_BAR; PG8_SCHED;
;             PG8_LDA(At, 0, 1); PG8_STAGE(PG8_SB(0, 0), b2, voffB); PG8_STAGE(PG8_SB(0, 1), b2 + hstepB, voffB); PG8_STAGE(PG8_SA(0, 0), a2, voffA);
.LBB0_176:
	ds_read_b128 v[144:147], v152
	ds_read_b128 v[156:159], v152 offset:1024
	ds_read_b128 v[160:163], v152 offset:2048
	ds_read_b128 v[164:167], v152 offset:3072
	ds_read_b128 v[168:171], v153
	ds_read_b128 v[172:175], v153 offset:1024
	ds_read_b128 v[176:179], v153 offset:2048
	ds_read_b128 v[180:183], v153 offset:3072
	s_add_u32 s28, s26, 0x100
	s_addc_u32 s29, s27, 0
	s_cmp_eq_u32 s53, 28
	s_cselect_b32 s35, s19, s29
	s_cselect_b32 s34, s49, s28
	s_cselect_b32 s31, s17, s52
	s_cselect_b32 s30, s50, s51
	v_lshl_add_u64 v[222:223], s[26:27], 0, v[136:137]
	s_add_i32 m0, s25, 0xc000
	ds_read_b128 v[190:193], v154
	ds_read_b128 v[194:197], v154 offset:1024
	ds_read_b128 v[198:201], v154 offset:2048
	ds_read_b128 v[202:205], v154 offset:3072
	ds_read_b128 v[206:209], v154 offset:4096
	ds_read_b128 v[210:213], v154 offset:5120
	ds_read_b128 v[214:217], v154 offset:6144
	ds_read_b128 v[218:221], v154 offset:7168
	global_load_lds_dwordx4 v[222:223], off
	v_lshl_add_u64 v[222:223], s[26:27], 0, v[138:139]
	s_add_i32 m0, s25, 0xe000
	s_nop 0
	global_load_lds_dwordx4 v[222:223], off
	s_waitcnt vmcnt(8)
	s_waitcnt lgkmcnt(0)
	s_barrier
	s_setprio 1
	s_waitcnt lgkmcnt(0)
	v_mfma_f32_16x16x32_bf16 v[124:127], v[144:147], v[190:193], v[124:127]
	v_mfma_f32_16x16x32_bf16 v[120:123], v[160:163], v[190:193], v[120:123]
	v_mfma_f32_16x16x32_bf16 v[116:119], v[144:147], v[198:201], v[116:119]
	v_mfma_f32_16x16x32_bf16 v[108:111], v[160:163], v[198:201], v[108:111]
	v_mfma_f32_16x16x32_bf16 v[100:103], v[144:147], v[206:209], v[100:103]
	v_mfma_f32_16x16x32_bf16 v[92:95], v[160:163], v[206:209], v[92:95]
	v_mfma_f32_16x16x32_bf16 v[84:87], v[144:147], v[214:217], v[84:87]
	v_mfma_f32_16x16x32_bf16 v[76:79], v[160:163], v[214:217], v[76:79]
	v_mfma_f32_16x16x32_bf16 v[124:127], v[156:159], v[194:197], v[124:127]
	v_mfma_f32_16x16x32_bf16 v[120:123], v[164:167], v[194:197], v[120:123]
	v_mfma_f32_16x16x32_bf16 v[116:119], v[156:159], v[202:205], v[116:119]
	v_mfma_f32_16x16x32_bf16 v[108:111], v[164:167], v[202:205], v[108:111]
	v_mfma_f32_16x16x32_bf16 v[100:103], v[156:159], v[210:213], v[100:103]
	v_mfma_f32_16x16x32_bf16 v[92:95], v[164:167], v[210:213], v[92:95]
	v_mfma_f32_16x16x32_bf16 v[84:87], v[156:159], v[218:221], v[84:87]
	v_mfma_f32_16x16x32_bf16 v[76:79], v[164:167], v[218:221], v[76:79]
	s_setprio 0
	s_setprio 1
	v_mfma_f32_16x16x32_bf16 v[112:115], v[168:171], v[190:193], v[112:115]
	v_mfma_f32_16x16x32_bf16 v[104:107], v[176:179], v[190:193], v[104:107]
	v_mfma_f32_16x16x32_bf16 v[96:99], v[168:171], v[198:201], v[96:99]
	v_mfma_f32_16x16x32_bf16 v[88:91], v[176:179], v[198:201], v[88:91]
	v_mfma_f32_16x16x32_bf16 v[80:83], v[168:171], v[206:209], v[80:83]
	v_mfma_f32_16x16x32_bf16 v[72:75], v[176:179], v[206:209], v[72:75]
	v_mfma_f32_16x16x32_bf16 v[68:71], v[168:171], v[214:217], v[68:71]
	v_mfma_f32_16x16x32_bf16 v[64:67], v[176:179], v[214:217], v[64:67]
	v_mfma_f32_16x16x32_bf16 v[112:115], v[172:175], v[194:197], v[112:115]
	v_mfma_f32_16x16x32_bf16 v[104:107], v[180:183], v[194:197], v[104:107]
	v_mfma_f32_16x16x32_bf16 v[96:99], v[172:175], v[202:205], v[96:99]
	v_mfma_f32_16x16x32_bf16 v[88:91], v[180:183], v[202:205], v[88:91]
	v_mfma_f32_16x16x32_bf16 v[80:83], v[172:175], v[210:213], v[80:83]
	v_mfma_f32_16x16x32_bf16 v[72:75], v[180:183], v[210:213], v[72:75]
	v_mfma_f32_16x16x32_bf16 v[68:71], v[172:175], v[218:221], v[68:71]
	v_mfma_f32_16x16x32_bf16 v[64:67], v[180:183], v[218:221], v[64:67]
	s_setprio 0
	s_barrier
	s_add_i32 s26, s45, s36
	v_lshl_add_u64 v[222:223], s[30:31], 0, v[130:131]
	s_mov_b32 m0, s26
	ds_read_b128 v[190:193], v154 offset:16384
	ds_read_b128 v[194:197], v154 offset:17408
	ds_read_b128 v[198:201], v154 offset:18432
	ds_read_b128 v[202:205], v154 offset:19456
	ds_read_b128 v[206:209], v154 offset:20480
	ds_read_b128 v[210:213], v154 offset:21504
	ds_read_b128 v[214:217], v154 offset:22528
	ds_read_b128 v[218:221], v154 offset:23552
	global_load_lds_dwordx4 v[222:223], off
	s_add_i32 m0, s26, 0x2000
	s_add_u32 s26, s30, 0x80000
	v_lshl_add_u64 v[224:225], s[30:31], 0, v[134:135]
	s_addc_u32 s27, s31, 0
	s_add_i32 s54, s46, s36
	global_load_lds_dwordx4 v[224:225], off
	v_lshl_add_u64 v[226:227], s[26:27], 0, v[130:131]
	s_mov_b32 m0, s54
	v_lshl_add_u64 v[228:229], s[34:35], 0, v[132:133]
	global_load_lds_dwordx4 v[226:227], off
	v_lshl_add_u64 v[226:227], s[26:27], 0, v[134:135]
	s_add_i32 m0, s54, 0x2000
	s_nop 0
	global_load_lds_dwordx4 v[226:227], off
	v_lshl_add_u64 v[226:227], s[34:35], 0, v[128:129]
	s_mov_b32 m0, s25
	s_nop 0
	global_load_lds_dwordx4 v[226:227], off
	s_mov_b32 m0, s37
	s_nop 0
	global_load_lds_dwordx4 v[228:229], off
	s_waitcnt vmcnt(8)
	s_waitcnt lgkmcnt(0)
	s_barrier
; #define PG8_STAGE(bufoff, gbase, voff) do { _Pragma("unroll") for (int _i = 0; _i < 2; ++_i) \
;         __builtin_amdgcn_global_load_lds((const unsigned*)((const char*)(gbase) + (voff)[_i]), (LAS unsigned*)(lds + (bufoff) + ldsw + _i * 8192), 16, 0, 0); } while (0)
; #define PG8_LDA(dst, b, h) do { _Pragma("unroll") for (int m = 0; m < 4; ++m) _Pragma("unroll") for (int k = 0; k < 2; ++k) dst[m][k] = *(const LAS bf16x8*)(lds + PG8_SA(b, h) + aoff + m * 2048 + k * 1024); } while (0)
; #define PG8_LDB(dst, b, h) do { _Pragma("unroll") for (int n = 0; n < 2; ++n) _Pragma("unroll") for (int k = 0; k < 2; ++k) dst[n][k] = *(const LAS bf16x8*)(lds + PG8_SB(b, h) + boff + n * 2048 + k * 1024); } while (0)
; #define PG8_MMA(ai, bj, At, Bt) do { __builtin_amdgcn_s_setprio(1); _Pragma("unroll") for (int m = 0; m < 4; ++m) _Pragma("unroll") for (int n = 0; n < 2; ++n) _Pragma("unroll") for (int k = 0; k < 2; ++k) \
;         acc[ai][bj][m][n] = __builtin_amdgcn_mfma_f32_16x16x32_bf16(Bt[n][k], At[m][k], acc[ai][bj][m][n], 0, 0, 0); __builtin_amdgcn_s_setprio(0); } while (0)
; #define PG8_WAIT_V(n) asm volatile("s_waitcnt vmcnt(" #n ")" ::: "memory")
; #define PG8_WAIT_L(n) asm volatile("s_waitcnt lgkmcnt(" #n ")" ::: "memory")
; #define PG8_BAR __builtin_amdgcn_s_barrier()
; #define PG8_SCHED __builtin_amdgcn_sched_barrier(0)
; template <class Epi, class Sched>
; __device__ __forceinline__ void gemm_phase(LAS unsigned char* lds, const Gemm g, const Sched& S, const Epi& E) {
;     ...
;             PG8_WAIT_V(8); PG8_WAIT_L(0); PG8_BAR; PG8_MMA(1, 0, At, B0); PG8_MMA(1, 1, At, B1); PG8_BAR; PG8_SCHED;
;             PG8_LDB(B0, 1, 0); PG8_LDB(B1, 1, 1); PG8_SCHED; PG8_LDA(At, 1, 0); PG8_STAGE(PG8_SA(0, 1), a2 + hstepA, voffA);
;             PG8_WAIT_V(8); PG8_WAIT_L(0); PG8_BAR; PG8_MMA(0, 0, At, B0); PG8_MMA(0, 1, At, B1); PG8_BAR; PG8_SCHED;
	s_setprio 1
	s_waitcnt lgkmcnt(0)
	v_mfma_f32_16x16x32_bf16 v[60:63], v[144:147], v[190:193], v[60:63]
	v_mfma_f32_16x16x32_bf16 v[56:59], v[160:163], v[190:193], v[56:59]
	v_mfma_f32_16x16x32_bf16 v[52:55], v[144:147], v[198:201], v[52:55]
	v_mfma_f32_16x16x32_bf16 v[44:47], v[160:163], v[198:201], v[44:47]
	v_mfma_f32_16x16x32_bf16 v[36:39], v[144:147], v[206:209], v[36:39]
	v_mfma_f32_16x16x32_bf16 v[28:31], v[160:163], v[206:209], v[28:31]
	v_mfma_f32_16x16x32_bf16 v[20:23], v[144:147], v[214:217], v[20:23]
	v_mfma_f32_16x16x32_bf16 v[12:15], v[160:163], v[214:217], v[12:15]
	v_mfma_f32_16x16x32_bf16 v[60:63], v[156:159], v[194:197], v[60:63]
	v_mfma_f32_16x16x32_bf16 v[56:59], v[164:167], v[194:197], v[56:59]
	v_mfma_f32_16x16x32_bf16 v[52:55], v[156:159], v[202:205], v[52:55]
	v_mfma_f32_16x16x32_bf16 v[44:47], v[164:167], v[202:205], v[44:47]
	v_mfma_f32_16x16x32_bf16 v[36:39], v[156:159], v[210:213], v[36:39]
	v_mfma_f32_16x16x32_bf16 v[28:31], v[164:167], v[210:213], v[28:31]
	v_mfma_f32_16x16x32_bf16 v[20:23], v[156:159], v[218:221], v[20:23]
	v_mfma_f32_16x16x32_bf16 v[12:15], v[164:167], v[218:221], v[12:15]
	s_setprio 0
	s_setprio 1
	v_mfma_f32_16x16x32_bf16 v[48:51], v[168:171], v[190:193], v[48:51]
	v_mfma_f32_16x16x32_bf16 v[40:43], v[176:179], v[190:193], v[40:43]
	v_mfma_f32_16x16x32_bf16 v[32:35], v[168:171], v[198:201], v[32:35]
	v_mfma_f32_16x16x32_bf16 v[24:27], v[176:179], v[198:201], v[24:27]
	v_mfma_f32_16x16x32_bf16 v[16:19], v[168:171], v[206:209], v[16:19]
	v_mfma_f32_16x16x32_bf16 v[8:11], v[176:179], v[206:209], v[8:11]
	v_mfma_f32_16x16x32_bf16 v[4:7], v[168:171], v[214:217], v[4:7]
	v_mfma_f32_16x16x32_bf16 v[0:3], v[176:179], v[214:217], v[0:3]
	v_mfma_f32_16x16x32_bf16 v[48:51], v[172:175], v[194:197], v[48:51]
	v_mfma_f32_16x16x32_bf16 v[40:43], v[180:183], v[194:197], v[40:43]
	v_mfma_f32_16x16x32_bf16 v[32:35], v[172:175], v[202:205], v[32:35]
	v_mfma_f32_16x16x32_bf16 v[24:27], v[180:183], v[202:205], v[24:27]
	v_mfma_f32_16x16x32_bf16 v[16:19], v[172:175], v[210:213], v[16:19]
	v_mfma_f32_16x16x32_bf16 v[8:11], v[180:183], v[210:213], v[8:11]
	v_mfma_f32_16x16x32_bf16 v[4:7], v[172:175], v[218:221], v[4:7]
	v_mfma_f32_16x16x32_bf16 v[0:3], v[180:183], v[218:221], v[0:3]
	s_setprio 0
	s_barrier
	s_add_i32 s54, 0, 0x18000
	v_add_u32_e32 v155, s54, v150
	s_add_i32 s55, 0, 0x1c000
	ds_read_b128 v[144:147], v155
	ds_read_b128 v[156:159], v155 offset:1024
	ds_read_b128 v[160:163], v155 offset:2048
	ds_read_b128 v[164:167], v155 offset:3072
	v_add_u32_e32 v155, s55, v150
	ds_read_b128 v[168:171], v155
	ds_read_b128 v[172:175], v155 offset:1024
	ds_read_b128 v[176:179], v155 offset:2048
	ds_read_b128 v[180:183], v155 offset:3072
	s_add_u32 s26, s34, 0x80000
	s_addc_u32 s27, s35, 0
	s_mov_b32 m0, s38
	v_lshl_add_u64 v[230:231], s[26:27], 0, v[128:129]
	ds_read_b128 v[190:193], v154 offset:32768
	ds_read_b128 v[194:197], v154 offset:33792
	ds_read_b128 v[198:201], v154 offset:34816
	ds_read_b128 v[202:205], v154 offset:35840
	ds_read_b128 v[206:209], v154 offset:36864
	ds_read_b128 v[210:213], v154 offset:37888
	ds_read_b128 v[214:217], v154 offset:38912
	ds_read_b128 v[218:221], v154 offset:39936
	global_load_lds_dwordx4 v[230:231], off
	v_lshl_add_u64 v[230:231], s[26:27], 0, v[132:133]
	s_mov_b32 m0, s39
	s_nop 0
	global_load_lds_dwordx4 v[230:231], off
	s_waitcnt vmcnt(8)
	s_waitcnt lgkmcnt(0)
	s_barrier
	s_setprio 1
	s_waitcnt lgkmcnt(0)
	v_mfma_f32_16x16x32_bf16 v[124:127], v[144:147], v[190:193], v[124:127]
	v_mfma_f32_16x16x32_bf16 v[120:123], v[160:163], v[190:193], v[120:123]
	v_mfma_f32_16x16x32_bf16 v[116:119], v[144:147], v[198:201], v[116:119]
	v_mfma_f32_16x16x32_bf16 v[108:111], v[160:163], v[198:201], v[108:111]
	v_mfma_f32_16x16x32_bf16 v[100:103], v[144:147], v[206:209], v[100:103]
	v_mfma_f32_16x16x32_bf16 v[92:95], v[160:163], v[206:209], v[92:95]
	v_mfma_f32_16x16x32_bf16 v[84:87], v[144:147], v[214:217], v[84:87]
	v_mfma_f32_16x16x32_bf16 v[76:79], v[160:163], v[214:217], v[76:79]
	v_mfma_f32_16x16x32_bf16 v[124:127], v[156:159], v[194:197], v[124:127]
	v_mfma_f32_16x16x32_bf16 v[120:123], v[164:167], v[194:197], v[120:123]
	v_mfma_f32_16x16x32_bf16 v[116:119], v[156:159], v[202:205], v[116:119]
	v_mfma_f32_16x16x32_bf16 v[108:111], v[164:167], v[202:205], v[108:111]
	v_mfma_f32_16x16x32_bf16 v[100:103], v[156:159], v[210:213], v[100:103]
	v_mfma_f32_16x16x32_bf16 v[92:95], v[164:167], v[210:213], v[92:95]
	v_mfma_f32_16x16x32_bf16 v[84:87], v[156:159], v[218:221], v[84:87]
	v_mfma_f32_16x16x32_bf16 v[76:79], v[164:167], v[218:221], v[76:79]
	s_setprio 0
	s_setprio 1
	v_mfma_f32_16x16x32_bf16 v[112:115], v[168:171], v[190:193], v[112:115]
	v_mfma_f32_16x16x32_bf16 v[104:107], v[176:179], v[190:193], v[104:107]
	v_mfma_f32_16x16x32_bf16 v[96:99], v[168:171], v[198:201], v[96:99]
	v_mfma_f32_16x16x32_bf16 v[88:91], v[176:179], v[198:201], v[88:91]
	v_mfma_f32_16x16x32_bf16 v[80:83], v[168:171], v[206:209], v[80:83]
	v_mfma_f32_16x16x32_bf16 v[72:75], v[176:179], v[206:209], v[72:75]
	v_mfma_f32_16x16x32_bf16 v[68:71], v[168:171], v[214:217], v[68:71]
	v_mfma_f32_16x16x32_bf16 v[64:67], v[176:179], v[214:217], v[64:67]
	v_mfma_f32_16x16x32_bf16 v[112:115], v[172:175], v[194:197], v[112:115]
	v_mfma_f32_16x16x32_bf16 v[104:107], v[180:183], v[194:197], v[104:107]
	v_mfma_f32_16x16x32_bf16 v[96:99], v[172:175], v[202:205], v[96:99]
	v_mfma_f32_16x16x32_bf16 v[88:91], v[180:183], v[202:205], v[88:91]
	v_mfma_f32_16x16x32_bf16 v[80:83], v[172:175], v[210:213], v[80:83]
	v_mfma_f32_16x16x32_bf16 v[72:75], v[180:183], v[210:213], v[72:75]
	v_mfma_f32_16x16x32_bf16 v[68:71], v[172:175], v[218:221], v[68:71]
	v_mfma_f32_16x16x32_bf16 v[64:67], v[180:183], v[218:221], v[64:67]
	s_setprio 0
	s_barrier
; #define PG8_STAGE(bufoff, gbase, voff) do { _Pragma("unroll") for (int _i = 0; _i < 2; ++_i) \
;         __builtin_amdgcn_global_load_lds((const unsigned*)((const char*)(gbase) + (voff)[_i]), (LAS unsigned*)(lds + (bufoff) + ldsw + _i * 8192), 16, 0, 0); } while (0)
; #define PG8_LDA(dst, b, h) do { _Pragma("unroll") for (int m = 0; m < 4; ++m) _Pragma("unroll") for (int k = 0; k < 2; ++k) dst[m][k] = *(const LAS bf16x8*)(lds + PG8_SA(b, h) + aoff + m * 2048 + k * 1024); } while (0)
; #define PG8_MMA(ai, bj, At, Bt) do { __builtin_amdgcn_s_setprio(1); _Pragma("unroll") for (int m = 0; m < 4; ++m) _Pragma("unroll") for (int n = 0; n < 2; ++n) _Pragma("unroll") for (int k = 0; k < 2; ++k) \
;         acc[ai][bj][m][n] = __builtin_amdgcn_mfma_f32_16x16x32_bf16(Bt[n][k], At[m][k], acc[ai][bj][m][n], 0, 0, 0); __builtin_amdgcn_s_setprio(0); } while (0)
; #define PG8_WAIT_V(n) asm volatile("s_waitcnt vmcnt(" #n ")" ::: "memory")
; #define PG8_WAIT_L(n) asm volatile("s_waitcnt lgkmcnt(" #n ")" ::: "memory")
; #define PG8_BAR __builtin_amdgcn_s_barrier()
; #define PG8_SCHED __builtin_amdgcn_sched_barrier(0)
; template <class Epi, class Sched>
; __device__ __forceinline__ void gemm_phase(LAS unsigned char* lds, const Gemm g, const Sched& S, const Epi& E) {
;     ...
;         for (int t = 0; t < nt; t += 2) {
;             const bool last = (t == nt - 2);
;     ...
;             PG8_LDA(At, 1, 1); PG8_STAGE(PG8_SB(1, 0), b3, voffB); PG8_STAGE(PG8_SB(1, 1), b3 + hstepB, voffB); PG8_STAGE(PG8_SA(1, 0), a3, voffA);
;             PG8_WAIT_V(8); PG8_WAIT_L(0); PG8_BAR; PG8_MMA(1, 0, At, B0); PG8_MMA(1, 1, At, B1); PG8_BAR; PG8_SCHED;
	s_add_i32 s26, s54, s36
	v_lshl_add_u64 v[222:223], v[222:223], 0, s[12:13]
	s_mov_b32 m0, s26
	ds_read_b128 v[190:193], v154 offset:49152
	ds_read_b128 v[194:197], v154 offset:50176
	ds_read_b128 v[198:201], v154 offset:51200
	ds_read_b128 v[202:205], v154 offset:52224
	ds_read_b128 v[206:209], v154 offset:53248
	ds_read_b128 v[210:213], v154 offset:54272
	ds_read_b128 v[214:217], v154 offset:55296
	ds_read_b128 v[218:221], v154 offset:56320
	global_load_lds_dwordx4 v[222:223], off
	s_add_i32 m0, s26, 0x2000
	s_add_u32 s26, s30, 0x80080
	v_lshl_add_u64 v[222:223], v[224:225], 0, s[12:13]
	s_addc_u32 s27, s31, 0
	s_add_i32 s30, s55, s36
	global_load_lds_dwordx4 v[222:223], off
	v_lshl_add_u64 v[222:223], s[26:27], 0, v[130:131]
	s_mov_b32 m0, s30
	s_nop 0
	global_load_lds_dwordx4 v[222:223], off
	v_lshl_add_u64 v[222:223], s[26:27], 0, v[134:135]
	s_add_i32 m0, s30, 0x2000
	s_nop 0
	global_load_lds_dwordx4 v[222:223], off
	v_lshl_add_u64 v[222:223], v[226:227], 0, s[12:13]
	s_mov_b32 m0, s41
	s_nop 0
	global_load_lds_dwordx4 v[222:223], off
	v_lshl_add_u64 v[222:223], v[228:229], 0, s[12:13]
	s_mov_b32 m0, s42
	s_nop 0
	global_load_lds_dwordx4 v[222:223], off
	s_waitcnt vmcnt(8)
	s_waitcnt lgkmcnt(0)
	s_barrier
	s_setprio 1
	s_waitcnt lgkmcnt(0)
	v_mfma_f32_16x16x32_bf16 v[60:63], v[144:147], v[190:193], v[60:63]
	v_mfma_f32_16x16x32_bf16 v[56:59], v[160:163], v[190:193], v[56:59]
	s_add_i32 s53, s53, 2
	v_mfma_f32_16x16x32_bf16 v[52:55], v[144:147], v[198:201], v[52:55]
	s_add_u32 s51, s51, 0x100
	v_mfma_f32_16x16x32_bf16 v[44:47], v[160:163], v[198:201], v[44:47]
	s_addc_u32 s52, s52, 0
	v_mfma_f32_16x16x32_bf16 v[36:39], v[144:147], v[206:209], v[36:39]
	s_mov_b64 s[26:27], s[28:29]
	v_mfma_f32_16x16x32_bf16 v[28:31], v[160:163], v[206:209], v[28:31]
	s_cmp_gt_u32 s53, 29
	v_mfma_f32_16x16x32_bf16 v[20:23], v[144:147], v[214:217], v[20:23]
	v_mfma_f32_16x16x32_bf16 v[12:15], v[160:163], v[214:217], v[12:15]
	v_mfma_f32_16x16x32_bf16 v[60:63], v[156:159], v[194:197], v[60:63]
	v_mfma_f32_16x16x32_bf16 v[56:59], v[164:167], v[194:197], v[56:59]
	v_mfma_f32_16x16x32_bf16 v[52:55], v[156:159], v[202:205], v[52:55]
	v_mfma_f32_16x16x32_bf16 v[44:47], v[164:167], v[202:205], v[44:47]
	v_mfma_f32_16x16x32_bf16 v[36:39], v[156:159], v[210:213], v[36:39]
	v_mfma_f32_16x16x32_bf16 v[28:31], v[164:167], v[210:213], v[28:31]
	v_mfma_f32_16x16x32_bf16 v[20:23], v[156:159], v[218:221], v[20:23]
	v_mfma_f32_16x16x32_bf16 v[12:15], v[164:167], v[218:221], v[12:15]
	s_setprio 0
	s_setprio 1
	v_mfma_f32_16x16x32_bf16 v[48:51], v[168:171], v[190:193], v[48:51]
	v_mfma_f32_16x16x32_bf16 v[40:43], v[176:179], v[190:193], v[40:43]
	v_mfma_f32_16x16x32_bf16 v[32:35], v[168:171], v[198:201], v[32:35]
	v_mfma_f32_16x16x32_bf16 v[24:27], v[176:179], v[198:201], v[24:27]
	v_mfma_f32_16x16x32_bf16 v[16:19], v[168:171], v[206:209], v[16:19]
	v_mfma_f32_16x16x32_bf16 v[8:11], v[176:179], v[206:209], v[8:11]
	v_mfma_f32_16x16x32_bf16 v[4:7], v[168:171], v[214:217], v[4:7]
	v_mfma_f32_16x16x32_bf16 v[0:3], v[176:179], v[214:217], v[0:3]
	v_mfma_f32_16x16x32_bf16 v[48:51], v[172:175], v[194:197], v[48:51]
	v_mfma_f32_16x16x32_bf16 v[40:43], v[180:183], v[194:197], v[40:43]
	v_mfma_f32_16x16x32_bf16 v[32:35], v[172:175], v[202:205], v[32:35]
	v_mfma_f32_16x16x32_bf16 v[24:27], v[180:183], v[202:205], v[24:27]
	v_mfma_f32_16x16x32_bf16 v[16:19], v[172:175], v[210:213], v[16:19]
	v_mfma_f32_16x16x32_bf16 v[8:11], v[180:183], v[210:213], v[8:11]
	v_mfma_f32_16x16x32_bf16 v[4:7], v[172:175], v[218:221], v[4:7]
	v_mfma_f32_16x16x32_bf16 v[0:3], v[180:183], v[218:221], v[0:3]
	s_setprio 0
	s_barrier
	s_cbranch_scc0 .LBB0_176
	s_and_b64 vcc, exec, s[14:15]
	s_cbranch_vccz .LBB0_179
	s_barrier

; #define PG8_STAGE(bufoff, gbase, voff) do { _Pragma("unroll") for (int _i = 0; _i < 2; ++_i) \
;         __builtin_amdgcn_global_load_lds((const unsigned*)((const char*)(gbase) + (voff)[_i]), (LAS unsigned*)(lds + (bufoff) + ldsw + _i * 8192), 16, 0, 0); } while (0)
; #define PG8_LDA(dst, b, h) do { _Pragma("unroll") for (int m = 0; m < 4; ++m) _Pragma("unroll") for (int k = 0; k < 2; ++k) dst[m][k] = *(const LAS bf16x8*)(lds + PG8_SA(b, h) + aoff + m * 2048 + k * 1024); } while (0)
; #define PG8_LDB(dst, b, h) do { _Pragma("unroll") for (int n = 0; n < 2; ++n) _Pragma("unroll") for (int k = 0; k < 2; ++k) dst[n][k] = *(const LAS bf16x8*)(lds + PG8_SB(b, h) + boff + n * 2048 + k * 1024); } while (0)
; #define PG8_MMA(ai, bj, At, Bt) do { __builtin_amdgcn_s_setprio(1); _Pragma("unroll") for (int m = 0; m < 4; ++m) _Pragma("unroll") for (int n = 0; n < 2; ++n) _Pragma("unroll") for (int k = 0; k < 2; ++k) \
;         acc[ai][bj][m][n] = __builtin_amdgcn_mfma_f32_16x16x32_bf16(Bt[n][k], At[m][k], acc[ai][bj][m][n], 0, 0, 0); __builtin_amdgcn_s_setprio(0); } while (0)
; #define PG8_WAIT_V(n) asm volatile("s_waitcnt vmcnt(" #n ")" ::: "memory")
; #define PG8_WAIT_L(n) asm volatile("s_waitcnt lgkmcnt(" #n ")" ::: "memory")
; #define PG8_BAR __builtin_amdgcn_s_barrier()
; #define PG8_SCHED __builtin_amdgcn_sched_barrier(0)
; template <class Epi, class Sched>
; __device__ __forceinline__ void gemm_phase(LAS unsigned char* lds, const Gemm g, const Sched& S, const Epi& E) {
;     ...
;         for (int t = 0; t < nt; t += 2) {
;             const bool last = (t == nt - 2);
;             const char* a1 = cA + (size_t)(t + 1) * kstep;
;             const char* a2 = last ? nA : cA + (size_t)(t + 2) * kstep; const char* b2 = last ? nB : cB + (size_t)(t + 2) * kstep;
;             const char* a3 = a2 + kstep; const char* b3 = b2 + kstep;
;             PG8_LDB(B0, 0, 0); PG8_LDB(B1, 0, 1); PG8_SCHED; PG8_LDA(At, 0, 0); PG8_STAGE(PG8_SA(1, 1), a1 + hstepA, voffA);
;             PG8_WAIT_V(8); PG8_WAIT_L(0); PG8_BAR; PG8_MMA(0, 0, At, B0); PG8_MMA(0, 1, At, B1); PG8_BAR; PG8_SCHED;
;             PG8_LDA(At, 0, 1); PG8_STAGE(PG8_SB(0, 0), b2, voffB); PG8_STAGE(PG8_SB(0, 1), b2 + hstepB, voffB); PG8_STAGE(PG8_SA(0, 0), a2, voffA);
.LBB0_669:
	ds_read_b128 v[104:107], v200
	ds_read_b128 v[116:119], v200 offset:1024
	ds_read_b128 v[128:131], v200 offset:2048
	ds_read_b128 v[140:143], v200 offset:3072
	ds_read_b128 v[144:147], v201
	ds_read_b128 v[148:151], v201 offset:1024
	ds_read_b128 v[152:155], v201 offset:2048
	ds_read_b128 v[164:167], v201 offset:3072
	s_add_u32 s6, s0, 0xfff40080
	s_addc_u32 s7, s1, -1
	s_cmp_eq_u32 s46, 12
	s_cselect_b32 s9, s23, s7
	s_cselect_b32 s8, s22, s6
	s_cselect_b32 s7, s25, s45
	s_cselect_b32 s6, s24, s44
	v_lshl_add_u64 v[220:221], s[0:1], 0, v[156:157]
	s_add_i32 m0, s27, 0xc000
	ds_read_b128 v[168:171], v202
	ds_read_b128 v[172:175], v202 offset:1024
	ds_read_b128 v[204:207], v202 offset:2048
	ds_read_b128 v[208:211], v202 offset:3072
	ds_read_b128 v[212:215], v202 offset:4096
	ds_read_b128 v[216:219], v202 offset:5120
	ds_read_b128 v[224:227], v202 offset:6144
	ds_read_b128 v[228:231], v202 offset:7168
	global_load_lds_dwordx4 v[220:221], off
	v_lshl_add_u64 v[220:221], s[0:1], 0, v[158:159]
	s_add_i32 m0, s27, 0xe000
	s_nop 0
	global_load_lds_dwordx4 v[220:221], off
	s_waitcnt vmcnt(8)
	s_waitcnt lgkmcnt(0)
	s_barrier
	s_setprio 1
	s_waitcnt lgkmcnt(0)
	v_mfma_f32_16x16x32_bf16 v[136:139], v[104:107], v[168:171], v[136:139]
	v_mfma_f32_16x16x32_bf16 v[132:135], v[128:131], v[168:171], v[132:135]
	v_mfma_f32_16x16x32_bf16 v[112:115], v[104:107], v[204:207], v[112:115]
	v_mfma_f32_16x16x32_bf16 v[108:111], v[128:131], v[204:207], v[108:111]
	v_mfma_f32_16x16x32_bf16 v[92:95], v[104:107], v[212:215], v[92:95]
	v_mfma_f32_16x16x32_bf16 v[88:91], v[128:131], v[212:215], v[88:91]
	v_mfma_f32_16x16x32_bf16 v[76:79], v[104:107], v[224:227], v[76:79]
	v_mfma_f32_16x16x32_bf16 v[72:75], v[128:131], v[224:227], v[72:75]
	v_mfma_f32_16x16x32_bf16 v[136:139], v[116:119], v[172:175], v[136:139]
	v_mfma_f32_16x16x32_bf16 v[132:135], v[140:143], v[172:175], v[132:135]
	v_mfma_f32_16x16x32_bf16 v[112:115], v[116:119], v[208:211], v[112:115]
	v_mfma_f32_16x16x32_bf16 v[108:111], v[140:143], v[208:211], v[108:111]
	v_mfma_f32_16x16x32_bf16 v[92:95], v[116:119], v[216:219], v[92:95]
	v_mfma_f32_16x16x32_bf16 v[88:91], v[140:143], v[216:219], v[88:91]
	v_mfma_f32_16x16x32_bf16 v[76:79], v[116:119], v[228:231], v[76:79]
	v_mfma_f32_16x16x32_bf16 v[72:75], v[140:143], v[228:231], v[72:75]
	s_setprio 0
	s_setprio 1
	v_mfma_f32_16x16x32_bf16 v[124:127], v[144:147], v[168:171], v[124:127]
	v_mfma_f32_16x16x32_bf16 v[120:123], v[152:155], v[168:171], v[120:123]
	v_mfma_f32_16x16x32_bf16 v[100:103], v[144:147], v[204:207], v[100:103]
	v_mfma_f32_16x16x32_bf16 v[96:99], v[152:155], v[204:207], v[96:99]
	v_mfma_f32_16x16x32_bf16 v[84:87], v[144:147], v[212:215], v[84:87]
	v_mfma_f32_16x16x32_bf16 v[80:83], v[152:155], v[212:215], v[80:83]
	v_mfma_f32_16x16x32_bf16 v[68:71], v[144:147], v[224:227], v[68:71]
	v_mfma_f32_16x16x32_bf16 v[64:67], v[152:155], v[224:227], v[64:67]
	v_mfma_f32_16x16x32_bf16 v[124:127], v[148:151], v[172:175], v[124:127]
	v_mfma_f32_16x16x32_bf16 v[120:123], v[164:167], v[172:175], v[120:123]
	v_mfma_f32_16x16x32_bf16 v[100:103], v[148:151], v[208:211], v[100:103]
	v_mfma_f32_16x16x32_bf16 v[96:99], v[164:167], v[208:211], v[96:99]
	v_mfma_f32_16x16x32_bf16 v[84:87], v[148:151], v[216:219], v[84:87]
	v_mfma_f32_16x16x32_bf16 v[80:83], v[164:167], v[216:219], v[80:83]
	v_mfma_f32_16x16x32_bf16 v[68:71], v[148:151], v[228:231], v[68:71]
	v_mfma_f32_16x16x32_bf16 v[64:67], v[164:167], v[228:231], v[64:67]
	s_setprio 0
	s_barrier
	s_add_i32 s47, s37, s26
	v_lshl_add_u64 v[220:221], s[6:7], 0, v[192:193]
	s_mov_b32 m0, s47
	ds_read_b128 v[168:171], v202 offset:16384
	ds_read_b128 v[172:175], v202 offset:17408
	ds_read_b128 v[204:207], v202 offset:18432
	ds_read_b128 v[208:211], v202 offset:19456
	ds_read_b128 v[212:215], v202 offset:20480
	ds_read_b128 v[216:219], v202 offset:21504
	ds_read_b128 v[224:227], v202 offset:22528
	ds_read_b128 v[228:231], v202 offset:23552
	global_load_lds_dwordx4 v[220:221], off
	s_add_i32 m0, s47, 0x2000
	s_add_u32 s48, s6, 0xc0000
	v_lshl_add_u64 v[232:233], s[6:7], 0, v[196:197]
	s_addc_u32 s49, s7, 0
	s_add_i32 s47, s38, s26
	global_load_lds_dwordx4 v[232:233], off
	v_lshl_add_u64 v[234:235], s[48:49], 0, v[192:193]
	s_mov_b32 m0, s47
	v_lshl_add_u64 v[236:237], s[8:9], 0, v[194:195]
	global_load_lds_dwordx4 v[234:235], off
	v_lshl_add_u64 v[234:235], s[48:49], 0, v[196:197]
	s_add_i32 m0, s47, 0x2000
	s_nop 0
	global_load_lds_dwordx4 v[234:235], off
	v_lshl_add_u64 v[234:235], s[8:9], 0, v[190:191]
	s_mov_b32 m0, s27
	s_nop 0
	global_load_lds_dwordx4 v[234:235], off
	s_mov_b32 m0, s28
	s_nop 0
	global_load_lds_dwordx4 v[236:237], off
	s_waitcnt vmcnt(8)
	s_waitcnt lgkmcnt(0)
	s_barrier
; #define PG8_STAGE(bufoff, gbase, voff) do { _Pragma("unroll") for (int _i = 0; _i < 2; ++_i) \
;         __builtin_amdgcn_global_load_lds((const unsigned*)((const char*)(gbase) + (voff)[_i]), (LAS unsigned*)(lds + (bufoff) + ldsw + _i * 8192), 16, 0, 0); } while (0)
; #define PG8_LDA(dst, b, h) do { _Pragma("unroll") for (int m = 0; m < 4; ++m) _Pragma("unroll") for (int k = 0; k < 2; ++k) dst[m][k] = *(const LAS bf16x8*)(lds + PG8_SA(b, h) + aoff + m * 2048 + k * 1024); } while (0)
; #define PG8_LDB(dst, b, h) do { _Pragma("unroll") for (int n = 0; n < 2; ++n) _Pragma("unroll") for (int k = 0; k < 2; ++k) dst[n][k] = *(const LAS bf16x8*)(lds + PG8_SB(b, h) + boff + n * 2048 + k * 1024); } while (0)
; #define PG8_MMA(ai, bj, At, Bt) do { __builtin_amdgcn_s_setprio(1); _Pragma("unroll") for (int m = 0; m < 4; ++m) _Pragma("unroll") for (int n = 0; n < 2; ++n) _Pragma("unroll") for (int k = 0; k < 2; ++k) \
;         acc[ai][bj][m][n] = __builtin_amdgcn_mfma_f32_16x16x32_bf16(Bt[n][k], At[m][k], acc[ai][bj][m][n], 0, 0, 0); __builtin_amdgcn_s_setprio(0); } while (0)
; #define PG8_WAIT_V(n) asm volatile("s_waitcnt vmcnt(" #n ")" ::: "memory")
; #define PG8_WAIT_L(n) asm volatile("s_waitcnt lgkmcnt(" #n ")" ::: "memory")
; #define PG8_BAR __builtin_amdgcn_s_barrier()
; #define PG8_SCHED __builtin_amdgcn_sched_barrier(0)
; template <class Epi, class Sched>
; __device__ __forceinline__ void gemm_phase(LAS unsigned char* lds, const Gemm g, const Sched& S, const Epi& E) {
;     ...
;             PG8_WAIT_V(8); PG8_WAIT_L(0); PG8_BAR; PG8_MMA(1, 0, At, B0); PG8_MMA(1, 1, At, B1); PG8_BAR; PG8_SCHED;
;             PG8_LDB(B0, 1, 0); PG8_LDB(B1, 1, 1); PG8_SCHED; PG8_LDA(At, 1, 0); PG8_STAGE(PG8_SA(0, 1), a2 + hstepA, voffA);
;             PG8_WAIT_V(8); PG8_WAIT_L(0); PG8_BAR; PG8_MMA(0, 0, At, B0); PG8_MMA(0, 1, At, B1); PG8_BAR; PG8_SCHED;
	s_setprio 1
	s_waitcnt lgkmcnt(0)
	v_mfma_f32_16x16x32_bf16 v[60:63], v[104:107], v[168:171], v[60:63]
	v_mfma_f32_16x16x32_bf16 v[56:59], v[128:131], v[168:171], v[56:59]
	v_mfma_f32_16x16x32_bf16 v[44:47], v[104:107], v[204:207], v[44:47]
	v_mfma_f32_16x16x32_bf16 v[40:43], v[128:131], v[204:207], v[40:43]
	v_mfma_f32_16x16x32_bf16 v[28:31], v[104:107], v[212:215], v[28:31]
	v_mfma_f32_16x16x32_bf16 v[24:27], v[128:131], v[212:215], v[24:27]
	v_mfma_f32_16x16x32_bf16 v[12:15], v[104:107], v[224:227], v[12:15]
	v_mfma_f32_16x16x32_bf16 v[8:11], v[128:131], v[224:227], v[8:11]
	v_mfma_f32_16x16x32_bf16 v[60:63], v[116:119], v[172:175], v[60:63]
	v_mfma_f32_16x16x32_bf16 v[56:59], v[140:143], v[172:175], v[56:59]
	v_mfma_f32_16x16x32_bf16 v[44:47], v[116:119], v[208:211], v[44:47]
	v_mfma_f32_16x16x32_bf16 v[40:43], v[140:143], v[208:211], v[40:43]
	v_mfma_f32_16x16x32_bf16 v[28:31], v[116:119], v[216:219], v[28:31]
	v_mfma_f32_16x16x32_bf16 v[24:27], v[140:143], v[216:219], v[24:27]
	v_mfma_f32_16x16x32_bf16 v[12:15], v[116:119], v[228:231], v[12:15]
	v_mfma_f32_16x16x32_bf16 v[8:11], v[140:143], v[228:231], v[8:11]
	s_setprio 0
	s_setprio 1
	v_mfma_f32_16x16x32_bf16 v[52:55], v[144:147], v[168:171], v[52:55]
	v_mfma_f32_16x16x32_bf16 v[48:51], v[152:155], v[168:171], v[48:51]
	v_mfma_f32_16x16x32_bf16 v[36:39], v[144:147], v[204:207], v[36:39]
	v_mfma_f32_16x16x32_bf16 v[32:35], v[152:155], v[204:207], v[32:35]
	v_mfma_f32_16x16x32_bf16 v[20:23], v[144:147], v[212:215], v[20:23]
	v_mfma_f32_16x16x32_bf16 v[16:19], v[152:155], v[212:215], v[16:19]
	v_mfma_f32_16x16x32_bf16 v[4:7], v[144:147], v[224:227], v[4:7]
	v_mfma_f32_16x16x32_bf16 v[0:3], v[152:155], v[224:227], v[0:3]
	v_mfma_f32_16x16x32_bf16 v[52:55], v[148:151], v[172:175], v[52:55]
	v_mfma_f32_16x16x32_bf16 v[48:51], v[164:167], v[172:175], v[48:51]
	v_mfma_f32_16x16x32_bf16 v[36:39], v[148:151], v[208:211], v[36:39]
	v_mfma_f32_16x16x32_bf16 v[32:35], v[164:167], v[208:211], v[32:35]
	v_mfma_f32_16x16x32_bf16 v[20:23], v[148:151], v[216:219], v[20:23]
	v_mfma_f32_16x16x32_bf16 v[16:19], v[164:167], v[216:219], v[16:19]
	v_mfma_f32_16x16x32_bf16 v[4:7], v[148:151], v[228:231], v[4:7]
	v_mfma_f32_16x16x32_bf16 v[0:3], v[164:167], v[228:231], v[0:3]
	s_setprio 0
	s_barrier
	s_add_i32 s47, 0, 0x18000
	s_add_i32 s48, 0, 0x1c000
	v_add_u32_e32 v140, s47, v198
	v_add_u32_e32 v164, s48, v198
	ds_read_b128 v[104:107], v140
	ds_read_b128 v[116:119], v140 offset:1024
	ds_read_b128 v[128:131], v140 offset:2048
	ds_read_b128 v[140:143], v140 offset:3072
	ds_read_b128 v[144:147], v164
	ds_read_b128 v[148:151], v164 offset:1024
	ds_read_b128 v[152:155], v164 offset:2048
	ds_read_b128 v[164:167], v164 offset:3072
	s_add_u32 s8, s8, 0xc0000
	s_addc_u32 s9, s9, 0
	s_mov_b32 m0, s29
	v_lshl_add_u64 v[238:239], s[8:9], 0, v[190:191]
	ds_read_b128 v[168:171], v202 offset:32768
	ds_read_b128 v[172:175], v202 offset:33792
	ds_read_b128 v[204:207], v202 offset:34816
	ds_read_b128 v[208:211], v202 offset:35840
	ds_read_b128 v[212:215], v202 offset:36864
	ds_read_b128 v[216:219], v202 offset:37888
	ds_read_b128 v[224:227], v202 offset:38912
	ds_read_b128 v[228:231], v202 offset:39936
	global_load_lds_dwordx4 v[238:239], off
	v_lshl_add_u64 v[238:239], s[8:9], 0, v[194:195]
	s_mov_b32 m0, s30
	s_nop 0
	global_load_lds_dwordx4 v[238:239], off
	s_waitcnt vmcnt(8)
	s_waitcnt lgkmcnt(0)
	s_barrier
	s_setprio 1
	s_waitcnt lgkmcnt(0)
	v_mfma_f32_16x16x32_bf16 v[136:139], v[104:107], v[168:171], v[136:139]
	v_mfma_f32_16x16x32_bf16 v[132:135], v[128:131], v[168:171], v[132:135]
	v_mfma_f32_16x16x32_bf16 v[112:115], v[104:107], v[204:207], v[112:115]
	v_mfma_f32_16x16x32_bf16 v[108:111], v[128:131], v[204:207], v[108:111]
	v_mfma_f32_16x16x32_bf16 v[92:95], v[104:107], v[212:215], v[92:95]
	v_mfma_f32_16x16x32_bf16 v[88:91], v[128:131], v[212:215], v[88:91]
	v_mfma_f32_16x16x32_bf16 v[76:79], v[104:107], v[224:227], v[76:79]
	v_mfma_f32_16x16x32_bf16 v[72:75], v[128:131], v[224:227], v[72:75]
	v_mfma_f32_16x16x32_bf16 v[136:139], v[116:119], v[172:175], v[136:139]
	v_mfma_f32_16x16x32_bf16 v[132:135], v[140:143], v[172:175], v[132:135]
	v_mfma_f32_16x16x32_bf16 v[112:115], v[116:119], v[208:211], v[112:115]
	v_mfma_f32_16x16x32_bf16 v[108:111], v[140:143], v[208:211], v[108:111]
	v_mfma_f32_16x16x32_bf16 v[92:95], v[116:119], v[216:219], v[92:95]
	v_mfma_f32_16x16x32_bf16 v[88:91], v[140:143], v[216:219], v[88:91]
	v_mfma_f32_16x16x32_bf16 v[76:79], v[116:119], v[228:231], v[76:79]
	v_mfma_f32_16x16x32_bf16 v[72:75], v[140:143], v[228:231], v[72:75]
	s_setprio 0
	s_setprio 1
	v_mfma_f32_16x16x32_bf16 v[124:127], v[144:147], v[168:171], v[124:127]
	v_mfma_f32_16x16x32_bf16 v[120:123], v[152:155], v[168:171], v[120:123]
	v_mfma_f32_16x16x32_bf16 v[100:103], v[144:147], v[204:207], v[100:103]
	v_mfma_f32_16x16x32_bf16 v[96:99], v[152:155], v[204:207], v[96:99]
	v_mfma_f32_16x16x32_bf16 v[84:87], v[144:147], v[212:215], v[84:87]
	v_mfma_f32_16x16x32_bf16 v[80:83], v[152:155], v[212:215], v[80:83]
	v_mfma_f32_16x16x32_bf16 v[68:71], v[144:147], v[224:227], v[68:71]
	v_mfma_f32_16x16x32_bf16 v[64:67], v[152:155], v[224:227], v[64:67]
	v_mfma_f32_16x16x32_bf16 v[124:127], v[148:151], v[172:175], v[124:127]
	v_mfma_f32_16x16x32_bf16 v[120:123], v[164:167], v[172:175], v[120:123]
	v_mfma_f32_16x16x32_bf16 v[100:103], v[148:151], v[208:211], v[100:103]
	v_mfma_f32_16x16x32_bf16 v[96:99], v[164:167], v[208:211], v[96:99]
	v_mfma_f32_16x16x32_bf16 v[84:87], v[148:151], v[216:219], v[84:87]
	v_mfma_f32_16x16x32_bf16 v[80:83], v[164:167], v[216:219], v[80:83]
	v_mfma_f32_16x16x32_bf16 v[68:71], v[148:151], v[228:231], v[68:71]
	v_mfma_f32_16x16x32_bf16 v[64:67], v[164:167], v[228:231], v[64:67]
	s_setprio 0
	s_barrier
; #define PG8_STAGE(bufoff, gbase, voff) do { _Pragma("unroll") for (int _i = 0; _i < 2; ++_i) \
;         __builtin_amdgcn_global_load_lds((const unsigned*)((const char*)(gbase) + (voff)[_i]), (LAS unsigned*)(lds + (bufoff) + ldsw + _i * 8192), 16, 0, 0); } while (0)
; #define PG8_LDA(dst, b, h) do { _Pragma("unroll") for (int m = 0; m < 4; ++m) _Pragma("unroll") for (int k = 0; k < 2; ++k) dst[m][k] = *(const LAS bf16x8*)(lds + PG8_SA(b, h) + aoff + m * 2048 + k * 1024); } while (0)
; #define PG8_MMA(ai, bj, At, Bt) do { __builtin_amdgcn_s_setprio(1); _Pragma("unroll") for (int m = 0; m < 4; ++m) _Pragma("unroll") for (int n = 0; n < 2; ++n) _Pragma("unroll") for (int k = 0; k < 2; ++k) \
;         acc[ai][bj][m][n] = __builtin_amdgcn_mfma_f32_16x16x32_bf16(Bt[n][k], At[m][k], acc[ai][bj][m][n], 0, 0, 0); __builtin_amdgcn_s_setprio(0); } while (0)
; #define PG8_WAIT_V(n) asm volatile("s_waitcnt vmcnt(" #n ")" ::: "memory")
; #define PG8_WAIT_L(n) asm volatile("s_waitcnt lgkmcnt(" #n ")" ::: "memory")
; #define PG8_BAR __builtin_amdgcn_s_barrier()
; #define PG8_SCHED __builtin_amdgcn_sched_barrier(0)
; template <class Epi, class Sched>
; __device__ __forceinline__ void gemm_phase(LAS unsigned char* lds, const Gemm g, const Sched& S, const Epi& E) {
;     ...
;         for (int t = 0; t < nt; t += 2) {
;             const bool last = (t == nt - 2);
;     ...
;             PG8_LDA(At, 1, 1); PG8_STAGE(PG8_SB(1, 0), b3, voffB); PG8_STAGE(PG8_SB(1, 1), b3 + hstepB, voffB); PG8_STAGE(PG8_SA(1, 0), a3, voffA);
;             PG8_WAIT_V(8); PG8_WAIT_L(0); PG8_BAR; PG8_MMA(1, 0, At, B0); PG8_MMA(1, 1, At, B1); PG8_BAR; PG8_SCHED;
	s_add_i32 s8, s47, s26
	v_lshl_add_u64 v[220:221], v[220:221], 0, s[18:19]
	s_mov_b32 m0, s8
	ds_read_b128 v[168:171], v202 offset:49152
	ds_read_b128 v[172:175], v202 offset:50176
	ds_read_b128 v[204:207], v202 offset:51200
	ds_read_b128 v[208:211], v202 offset:52224
	ds_read_b128 v[212:215], v202 offset:53248
	ds_read_b128 v[216:219], v202 offset:54272
	ds_read_b128 v[224:227], v202 offset:55296
	ds_read_b128 v[228:231], v202 offset:56320
	global_load_lds_dwordx4 v[220:221], off
	s_add_i32 m0, s8, 0x2000
	s_add_u32 s6, s6, 0xc0080
	v_lshl_add_u64 v[220:221], v[232:233], 0, s[18:19]
	s_addc_u32 s7, s7, 0
	s_add_i32 s8, s48, s26
	global_load_lds_dwordx4 v[220:221], off
	v_lshl_add_u64 v[220:221], s[6:7], 0, v[192:193]
	s_mov_b32 m0, s8
	s_nop 0
	global_load_lds_dwordx4 v[220:221], off
	v_lshl_add_u64 v[220:221], s[6:7], 0, v[196:197]
	s_add_i32 m0, s8, 0x2000
	s_nop 0
	global_load_lds_dwordx4 v[220:221], off
	v_lshl_add_u64 v[220:221], v[234:235], 0, s[18:19]
	s_mov_b32 m0, s33
	s_nop 0
	global_load_lds_dwordx4 v[220:221], off
	v_lshl_add_u64 v[220:221], v[236:237], 0, s[18:19]
	s_mov_b32 m0, s34
	s_nop 0
	global_load_lds_dwordx4 v[220:221], off
	s_waitcnt vmcnt(8)
	s_waitcnt lgkmcnt(0)
	s_barrier
	s_setprio 1
	s_waitcnt lgkmcnt(0)
	v_mfma_f32_16x16x32_bf16 v[60:63], v[104:107], v[168:171], v[60:63]
	v_mfma_f32_16x16x32_bf16 v[56:59], v[128:131], v[168:171], v[56:59]
	s_add_i32 s46, s46, 2
	v_mfma_f32_16x16x32_bf16 v[44:47], v[104:107], v[204:207], v[44:47]
	s_add_u32 s0, s0, 0x100
	v_mfma_f32_16x16x32_bf16 v[40:43], v[128:131], v[204:207], v[40:43]
	s_addc_u32 s1, s1, 0
	v_mfma_f32_16x16x32_bf16 v[28:31], v[104:107], v[212:215], v[28:31]
	s_add_u32 s44, s44, 0x100
	v_mfma_f32_16x16x32_bf16 v[24:27], v[128:131], v[212:215], v[24:27]
	s_addc_u32 s45, s45, 0
	v_mfma_f32_16x16x32_bf16 v[12:15], v[104:107], v[224:227], v[12:15]
	s_cmp_gt_u32 s46, 13
	v_mfma_f32_16x16x32_bf16 v[8:11], v[128:131], v[224:227], v[8:11]
	v_mfma_f32_16x16x32_bf16 v[60:63], v[116:119], v[172:175], v[60:63]
	v_mfma_f32_16x16x32_bf16 v[56:59], v[140:143], v[172:175], v[56:59]
	v_mfma_f32_16x16x32_bf16 v[44:47], v[116:119], v[208:211], v[44:47]
	v_mfma_f32_16x16x32_bf16 v[40:43], v[140:143], v[208:211], v[40:43]
	v_mfma_f32_16x16x32_bf16 v[28:31], v[116:119], v[216:219], v[28:31]
	v_mfma_f32_16x16x32_bf16 v[24:27], v[140:143], v[216:219], v[24:27]
	v_mfma_f32_16x16x32_bf16 v[12:15], v[116:119], v[228:231], v[12:15]
	v_mfma_f32_16x16x32_bf16 v[8:11], v[140:143], v[228:231], v[8:11]
	s_setprio 0
	s_setprio 1
	v_mfma_f32_16x16x32_bf16 v[52:55], v[144:147], v[168:171], v[52:55]
	v_mfma_f32_16x16x32_bf16 v[48:51], v[152:155], v[168:171], v[48:51]
	v_mfma_f32_16x16x32_bf16 v[36:39], v[144:147], v[204:207], v[36:39]
	v_mfma_f32_16x16x32_bf16 v[32:35], v[152:155], v[204:207], v[32:35]
	v_mfma_f32_16x16x32_bf16 v[20:23], v[144:147], v[212:215], v[20:23]
	v_mfma_f32_16x16x32_bf16 v[16:19], v[152:155], v[212:215], v[16:19]
	v_mfma_f32_16x16x32_bf16 v[4:7], v[144:147], v[224:227], v[4:7]
	v_mfma_f32_16x16x32_bf16 v[0:3], v[152:155], v[224:227], v[0:3]
	v_mfma_f32_16x16x32_bf16 v[52:55], v[148:151], v[172:175], v[52:55]
	v_mfma_f32_16x16x32_bf16 v[48:51], v[164:167], v[172:175], v[48:51]
	v_mfma_f32_16x16x32_bf16 v[36:39], v[148:151], v[208:211], v[36:39]
	v_mfma_f32_16x16x32_bf16 v[32:35], v[164:167], v[208:211], v[32:35]
	v_mfma_f32_16x16x32_bf16 v[20:23], v[148:151], v[216:219], v[20:23]
	v_mfma_f32_16x16x32_bf16 v[16:19], v[164:167], v[216:219], v[16:19]
	v_mfma_f32_16x16x32_bf16 v[4:7], v[148:151], v[228:231], v[4:7]
	v_mfma_f32_16x16x32_bf16 v[0:3], v[164:167], v[228:231], v[0:3]
	s_setprio 0
	s_barrier
	s_cbranch_scc0 .LBB0_669
	s_and_b64 vcc, exec, s[20:21]
	s_cbranch_vccz .LBB0_672
	s_barrier

; #define PG8_STAGE(bufoff, gbase, voff) do { _Pragma("unroll") for (int _i = 0; _i < 2; ++_i) \
;         __builtin_amdgcn_global_load_lds((const unsigned*)((const char*)(gbase) + (voff)[_i]), (LAS unsigned*)(lds + (bufoff) + ldsw + _i * 8192), 16, 0, 0); } while (0)
; #define PG8_LDA(dst, b, h) do { _Pragma("unroll") for (int m = 0; m < 4; ++m) _Pragma("unroll") for (int k = 0; k < 2; ++k) dst[m][k] = *(const LAS bf16x8*)(lds + PG8_SA(b, h) + aoff + m * 2048 + k * 1024); } while (0)
; #define PG8_LDB(dst, b, h) do { _Pragma("unroll") for (int n = 0; n < 2; ++n) _Pragma("unroll") for (int k = 0; k < 2; ++k) dst[n][k] = *(const LAS bf16x8*)(lds + PG8_SB(b, h) + boff + n * 2048 + k * 1024); } while (0)
; #define PG8_MMA(ai, bj, At, Bt) do { __builtin_amdgcn_s_setprio(1); _Pragma("unroll") for (int m = 0; m < 4; ++m) _Pragma("unroll") for (int n = 0; n < 2; ++n) _Pragma("unroll") for (int k = 0; k < 2; ++k) \
;         acc[ai][bj][m][n] = __builtin_amdgcn_mfma_f32_16x16x32_bf16(Bt[n][k], At[m][k], acc[ai][bj][m][n], 0, 0, 0); __builtin_amdgcn_s_setprio(0); } while (0)
; #define PG8_WAIT_V(n) asm volatile("s_waitcnt vmcnt(" #n ")" ::: "memory")
; #define PG8_WAIT_L(n) asm volatile("s_waitcnt lgkmcnt(" #n ")" ::: "memory")
; #define PG8_BAR __builtin_amdgcn_s_barrier()
; #define PG8_SCHED __builtin_amdgcn_sched_barrier(0)
; template <class Epi, class Sched>
; __device__ __forceinline__ void gemm_phase(LAS unsigned char* lds, const Gemm g, const Sched& S, const Epi& E) {
;     ...
;         for (int t = 0; t < nt; t += 2) {
;             const bool last = (t == nt - 2);
;             const char* a1 = cA + (size_t)(t + 1) * kstep;
;             const char* a2 = last ? nA : cA + (size_t)(t + 2) * kstep; const char* b2 = last ? nB : cB + (size_t)(t + 2) * kstep;
;             const char* a3 = a2 + kstep; const char* b3 = b2 + kstep;
;             PG8_LDB(B0, 0, 0); PG8_LDB(B1, 0, 1); PG8_SCHED; PG8_LDA(At, 0, 0); PG8_STAGE(PG8_SA(1, 1), a1 + hstepA, voffA);
;             PG8_WAIT_V(8); PG8_WAIT_L(0); PG8_BAR; PG8_MMA(0, 0, At, B0); PG8_MMA(0, 1, At, B1); PG8_BAR; PG8_SCHED;
;             PG8_LDA(At, 0, 1); PG8_STAGE(PG8_SB(0, 0), b2, voffB); PG8_STAGE(PG8_SB(0, 1), b2 + hstepB, voffB); PG8_STAGE(PG8_SA(0, 0), a2, voffA);
.LBB0_697:
	ds_read_b128 v[88:91], v226
	ds_read_b128 v[92:95], v226 offset:1024
	ds_read_b128 v[104:107], v226 offset:2048
	ds_read_b128 v[108:111], v226 offset:3072
	ds_read_b128 v[120:123], v227
	ds_read_b128 v[124:127], v227 offset:1024
	ds_read_b128 v[136:139], v227 offset:2048
	ds_read_b128 v[140:143], v227 offset:3072
	s_add_u32 s20, s18, 0xfff40080
	s_addc_u32 s21, s19, -1
	s_cmp_eq_u32 s48, 28
	s_cselect_b32 s23, s7, s21
	s_cselect_b32 s22, s6, s20
	s_cselect_b32 s21, s17, s47
	s_cselect_b32 s20, s16, s46
	v_lshl_add_u64 v[214:215], s[18:19], 0, v[198:199]
	s_add_i32 m0, s29, 0xc000
	ds_read_b128 v[152:155], v228
	ds_read_b128 v[156:159], v228 offset:1024
	ds_read_b128 v[168:171], v228 offset:2048
	ds_read_b128 v[172:175], v228 offset:3072
	ds_read_b128 v[176:179], v228 offset:4096
	ds_read_b128 v[180:183], v228 offset:5120
	ds_read_b128 v[206:209], v228 offset:6144
	ds_read_b128 v[210:213], v228 offset:7168
	global_load_lds_dwordx4 v[214:215], off
	v_lshl_add_u64 v[214:215], s[18:19], 0, v[200:201]
	s_add_i32 m0, s29, 0xe000
	s_nop 0
	global_load_lds_dwordx4 v[214:215], off
	s_waitcnt vmcnt(8)
	s_waitcnt lgkmcnt(0)
	s_barrier
	s_setprio 1
	s_waitcnt lgkmcnt(0)
	v_mfma_f32_16x16x32_bf16 v[164:167], v[88:91], v[152:155], v[164:167]
	v_mfma_f32_16x16x32_bf16 v[160:163], v[104:107], v[152:155], v[160:163]
	v_mfma_f32_16x16x32_bf16 v[132:135], v[88:91], v[168:171], v[132:135]
	v_mfma_f32_16x16x32_bf16 v[128:131], v[104:107], v[168:171], v[128:131]
	v_mfma_f32_16x16x32_bf16 v[100:103], v[88:91], v[176:179], v[100:103]
	v_mfma_f32_16x16x32_bf16 v[96:99], v[104:107], v[176:179], v[96:99]
	v_mfma_f32_16x16x32_bf16 v[76:79], v[88:91], v[206:209], v[76:79]
	v_mfma_f32_16x16x32_bf16 v[72:75], v[104:107], v[206:209], v[72:75]
	v_mfma_f32_16x16x32_bf16 v[164:167], v[92:95], v[156:159], v[164:167]
	v_mfma_f32_16x16x32_bf16 v[160:163], v[108:111], v[156:159], v[160:163]
	v_mfma_f32_16x16x32_bf16 v[132:135], v[92:95], v[172:175], v[132:135]
	v_mfma_f32_16x16x32_bf16 v[128:131], v[108:111], v[172:175], v[128:131]
	v_mfma_f32_16x16x32_bf16 v[100:103], v[92:95], v[180:183], v[100:103]
	v_mfma_f32_16x16x32_bf16 v[96:99], v[108:111], v[180:183], v[96:99]
	v_mfma_f32_16x16x32_bf16 v[76:79], v[92:95], v[210:213], v[76:79]
	v_mfma_f32_16x16x32_bf16 v[72:75], v[108:111], v[210:213], v[72:75]
	s_setprio 0
	s_setprio 1
	v_mfma_f32_16x16x32_bf16 v[148:151], v[120:123], v[152:155], v[148:151]
	v_mfma_f32_16x16x32_bf16 v[144:147], v[136:139], v[152:155], v[144:147]
	v_mfma_f32_16x16x32_bf16 v[116:119], v[120:123], v[168:171], v[116:119]
	v_mfma_f32_16x16x32_bf16 v[112:115], v[136:139], v[168:171], v[112:115]
	v_mfma_f32_16x16x32_bf16 v[84:87], v[120:123], v[176:179], v[84:87]
	v_mfma_f32_16x16x32_bf16 v[80:83], v[136:139], v[176:179], v[80:83]
	v_mfma_f32_16x16x32_bf16 v[68:71], v[120:123], v[206:209], v[68:71]
	v_mfma_f32_16x16x32_bf16 v[64:67], v[136:139], v[206:209], v[64:67]
	v_mfma_f32_16x16x32_bf16 v[148:151], v[124:127], v[156:159], v[148:151]
	v_mfma_f32_16x16x32_bf16 v[144:147], v[140:143], v[156:159], v[144:147]
	v_mfma_f32_16x16x32_bf16 v[116:119], v[124:127], v[172:175], v[116:119]
	v_mfma_f32_16x16x32_bf16 v[112:115], v[140:143], v[172:175], v[112:115]
	v_mfma_f32_16x16x32_bf16 v[84:87], v[124:127], v[180:183], v[84:87]
	v_mfma_f32_16x16x32_bf16 v[80:83], v[140:143], v[180:183], v[80:83]
	v_mfma_f32_16x16x32_bf16 v[68:71], v[124:127], v[210:213], v[68:71]
	v_mfma_f32_16x16x32_bf16 v[64:67], v[140:143], v[210:213], v[64:67]
	s_setprio 0
	s_barrier
	s_add_i32 s49, s39, s28
	v_lshl_add_u64 v[214:215], s[20:21], 0, v[192:193]
	s_mov_b32 m0, s49
	ds_read_b128 v[152:155], v228 offset:16384
	ds_read_b128 v[156:159], v228 offset:17408
	ds_read_b128 v[168:171], v228 offset:18432
	ds_read_b128 v[172:175], v228 offset:19456
	ds_read_b128 v[176:179], v228 offset:20480
	ds_read_b128 v[180:183], v228 offset:21504
	ds_read_b128 v[206:209], v228 offset:22528
	ds_read_b128 v[210:213], v228 offset:23552
	global_load_lds_dwordx4 v[214:215], off
	s_add_i32 m0, s49, 0x2000
	s_add_u32 s50, s20, 0xc0000
	v_lshl_add_u64 v[216:217], s[20:21], 0, v[196:197]
	s_addc_u32 s51, s21, 0
	s_add_i32 s49, s40, s28
	global_load_lds_dwordx4 v[216:217], off
	v_lshl_add_u64 v[218:219], s[50:51], 0, v[192:193]
	s_mov_b32 m0, s49
	v_lshl_add_u64 v[220:221], s[22:23], 0, v[194:195]
	global_load_lds_dwordx4 v[218:219], off
	v_lshl_add_u64 v[218:219], s[50:51], 0, v[196:197]
	s_add_i32 m0, s49, 0x2000
	s_nop 0
	global_load_lds_dwordx4 v[218:219], off
	v_lshl_add_u64 v[218:219], s[22:23], 0, v[190:191]
	s_mov_b32 m0, s29
	s_nop 0
	global_load_lds_dwordx4 v[218:219], off
	s_mov_b32 m0, s30
	s_nop 0
	global_load_lds_dwordx4 v[220:221], off
	s_waitcnt vmcnt(8)
	s_waitcnt lgkmcnt(0)
	s_barrier
; #define PG8_STAGE(bufoff, gbase, voff) do { _Pragma("unroll") for (int _i = 0; _i < 2; ++_i) \
;         __builtin_amdgcn_global_load_lds((const unsigned*)((const char*)(gbase) + (voff)[_i]), (LAS unsigned*)(lds + (bufoff) + ldsw + _i * 8192), 16, 0, 0); } while (0)
; #define PG8_LDA(dst, b, h) do { _Pragma("unroll") for (int m = 0; m < 4; ++m) _Pragma("unroll") for (int k = 0; k < 2; ++k) dst[m][k] = *(const LAS bf16x8*)(lds + PG8_SA(b, h) + aoff + m * 2048 + k * 1024); } while (0)
; #define PG8_LDB(dst, b, h) do { _Pragma("unroll") for (int n = 0; n < 2; ++n) _Pragma("unroll") for (int k = 0; k < 2; ++k) dst[n][k] = *(const LAS bf16x8*)(lds + PG8_SB(b, h) + boff + n * 2048 + k * 1024); } while (0)
; #define PG8_MMA(ai, bj, At, Bt) do { __builtin_amdgcn_s_setprio(1); _Pragma("unroll") for (int m = 0; m < 4; ++m) _Pragma("unroll") for (int n = 0; n < 2; ++n) _Pragma("unroll") for (int k = 0; k < 2; ++k) \
;         acc[ai][bj][m][n] = __builtin_amdgcn_mfma_f32_16x16x32_bf16(Bt[n][k], At[m][k], acc[ai][bj][m][n], 0, 0, 0); __builtin_amdgcn_s_setprio(0); } while (0)
; #define PG8_WAIT_V(n) asm volatile("s_waitcnt vmcnt(" #n ")" ::: "memory")
; #define PG8_WAIT_L(n) asm volatile("s_waitcnt lgkmcnt(" #n ")" ::: "memory")
; #define PG8_BAR __builtin_amdgcn_s_barrier()
; #define PG8_SCHED __builtin_amdgcn_sched_barrier(0)
; template <class Epi, class Sched>
; __device__ __forceinline__ void gemm_phase(LAS unsigned char* lds, const Gemm g, const Sched& S, const Epi& E) {
;     ...
;             PG8_WAIT_V(8); PG8_WAIT_L(0); PG8_BAR; PG8_MMA(1, 0, At, B0); PG8_MMA(1, 1, At, B1); PG8_BAR; PG8_SCHED;
;             PG8_LDB(B0, 1, 0); PG8_LDB(B1, 1, 1); PG8_SCHED; PG8_LDA(At, 1, 0); PG8_STAGE(PG8_SA(0, 1), a2 + hstepA, voffA);
;             PG8_WAIT_V(8); PG8_WAIT_L(0); PG8_BAR; PG8_MMA(0, 0, At, B0); PG8_MMA(0, 1, At, B1); PG8_BAR; PG8_SCHED;
	s_setprio 1
	s_waitcnt lgkmcnt(0)
	v_mfma_f32_16x16x32_bf16 v[60:63], v[88:91], v[152:155], v[60:63]
	v_mfma_f32_16x16x32_bf16 v[56:59], v[104:107], v[152:155], v[56:59]
	v_mfma_f32_16x16x32_bf16 v[44:47], v[88:91], v[168:171], v[44:47]
	v_mfma_f32_16x16x32_bf16 v[40:43], v[104:107], v[168:171], v[40:43]
	v_mfma_f32_16x16x32_bf16 v[28:31], v[88:91], v[176:179], v[28:31]
	v_mfma_f32_16x16x32_bf16 v[24:27], v[104:107], v[176:179], v[24:27]
	v_mfma_f32_16x16x32_bf16 v[12:15], v[88:91], v[206:209], v[12:15]
	v_mfma_f32_16x16x32_bf16 v[8:11], v[104:107], v[206:209], v[8:11]
	v_mfma_f32_16x16x32_bf16 v[60:63], v[92:95], v[156:159], v[60:63]
	v_mfma_f32_16x16x32_bf16 v[56:59], v[108:111], v[156:159], v[56:59]
	v_mfma_f32_16x16x32_bf16 v[44:47], v[92:95], v[172:175], v[44:47]
	v_mfma_f32_16x16x32_bf16 v[40:43], v[108:111], v[172:175], v[40:43]
	v_mfma_f32_16x16x32_bf16 v[28:31], v[92:95], v[180:183], v[28:31]
	v_mfma_f32_16x16x32_bf16 v[24:27], v[108:111], v[180:183], v[24:27]
	v_mfma_f32_16x16x32_bf16 v[12:15], v[92:95], v[210:213], v[12:15]
	v_mfma_f32_16x16x32_bf16 v[8:11], v[108:111], v[210:213], v[8:11]
	s_setprio 0
	s_setprio 1
	v_mfma_f32_16x16x32_bf16 v[52:55], v[120:123], v[152:155], v[52:55]
	v_mfma_f32_16x16x32_bf16 v[48:51], v[136:139], v[152:155], v[48:51]
	v_mfma_f32_16x16x32_bf16 v[36:39], v[120:123], v[168:171], v[36:39]
	v_mfma_f32_16x16x32_bf16 v[32:35], v[136:139], v[168:171], v[32:35]
	v_mfma_f32_16x16x32_bf16 v[20:23], v[120:123], v[176:179], v[20:23]
	v_mfma_f32_16x16x32_bf16 v[16:19], v[136:139], v[176:179], v[16:19]
	v_mfma_f32_16x16x32_bf16 v[4:7], v[120:123], v[206:209], v[4:7]
	v_mfma_f32_16x16x32_bf16 v[0:3], v[136:139], v[206:209], v[0:3]
	v_mfma_f32_16x16x32_bf16 v[52:55], v[124:127], v[156:159], v[52:55]
	v_mfma_f32_16x16x32_bf16 v[48:51], v[140:143], v[156:159], v[48:51]
	v_mfma_f32_16x16x32_bf16 v[36:39], v[124:127], v[172:175], v[36:39]
	v_mfma_f32_16x16x32_bf16 v[32:35], v[140:143], v[172:175], v[32:35]
	v_mfma_f32_16x16x32_bf16 v[20:23], v[124:127], v[180:183], v[20:23]
	v_mfma_f32_16x16x32_bf16 v[16:19], v[140:143], v[180:183], v[16:19]
	v_mfma_f32_16x16x32_bf16 v[4:7], v[124:127], v[210:213], v[4:7]
	v_mfma_f32_16x16x32_bf16 v[0:3], v[140:143], v[210:213], v[0:3]
	s_setprio 0
	s_barrier
	s_add_i32 s49, 0, 0x18000
	s_add_i32 s50, 0, 0x1c000
	v_add_u32_e32 v108, s49, v224
	v_add_u32_e32 v140, s50, v224
	ds_read_b128 v[88:91], v108
	ds_read_b128 v[92:95], v108 offset:1024
	ds_read_b128 v[104:107], v108 offset:2048
	ds_read_b128 v[108:111], v108 offset:3072
	ds_read_b128 v[120:123], v140
	ds_read_b128 v[124:127], v140 offset:1024
	ds_read_b128 v[136:139], v140 offset:2048
	ds_read_b128 v[140:143], v140 offset:3072
	s_add_u32 s22, s22, 0xc0000
	s_addc_u32 s23, s23, 0
	s_mov_b32 m0, s31
	v_lshl_add_u64 v[230:231], s[22:23], 0, v[190:191]
	ds_read_b128 v[152:155], v228 offset:32768
	ds_read_b128 v[156:159], v228 offset:33792
	ds_read_b128 v[168:171], v228 offset:34816
	ds_read_b128 v[172:175], v228 offset:35840
	ds_read_b128 v[176:179], v228 offset:36864
	ds_read_b128 v[180:183], v228 offset:37888
	ds_read_b128 v[206:209], v228 offset:38912
	ds_read_b128 v[210:213], v228 offset:39936
	global_load_lds_dwordx4 v[230:231], off
	v_lshl_add_u64 v[230:231], s[22:23], 0, v[194:195]
	s_mov_b32 m0, s33
	s_nop 0
	global_load_lds_dwordx4 v[230:231], off
	s_waitcnt vmcnt(8)
	s_waitcnt lgkmcnt(0)
	s_barrier
	s_setprio 1
	s_waitcnt lgkmcnt(0)
	v_mfma_f32_16x16x32_bf16 v[164:167], v[88:91], v[152:155], v[164:167]
	v_mfma_f32_16x16x32_bf16 v[160:163], v[104:107], v[152:155], v[160:163]
	v_mfma_f32_16x16x32_bf16 v[132:135], v[88:91], v[168:171], v[132:135]
	v_mfma_f32_16x16x32_bf16 v[128:131], v[104:107], v[168:171], v[128:131]
	v_mfma_f32_16x16x32_bf16 v[100:103], v[88:91], v[176:179], v[100:103]
	v_mfma_f32_16x16x32_bf16 v[96:99], v[104:107], v[176:179], v[96:99]
	v_mfma_f32_16x16x32_bf16 v[76:79], v[88:91], v[206:209], v[76:79]
	v_mfma_f32_16x16x32_bf16 v[72:75], v[104:107], v[206:209], v[72:75]
	v_mfma_f32_16x16x32_bf16 v[164:167], v[92:95], v[156:159], v[164:167]
	v_mfma_f32_16x16x32_bf16 v[160:163], v[108:111], v[156:159], v[160:163]
	v_mfma_f32_16x16x32_bf16 v[132:135], v[92:95], v[172:175], v[132:135]
	v_mfma_f32_16x16x32_bf16 v[128:131], v[108:111], v[172:175], v[128:131]
	v_mfma_f32_16x16x32_bf16 v[100:103], v[92:95], v[180:183], v[100:103]
	v_mfma_f32_16x16x32_bf16 v[96:99], v[108:111], v[180:183], v[96:99]
	v_mfma_f32_16x16x32_bf16 v[76:79], v[92:95], v[210:213], v[76:79]
	v_mfma_f32_16x16x32_bf16 v[72:75], v[108:111], v[210:213], v[72:75]
	s_setprio 0
	s_setprio 1
	v_mfma_f32_16x16x32_bf16 v[148:151], v[120:123], v[152:155], v[148:151]
	v_mfma_f32_16x16x32_bf16 v[144:147], v[136:139], v[152:155], v[144:147]
	v_mfma_f32_16x16x32_bf16 v[116:119], v[120:123], v[168:171], v[116:119]
	v_mfma_f32_16x16x32_bf16 v[112:115], v[136:139], v[168:171], v[112:115]
	v_mfma_f32_16x16x32_bf16 v[84:87], v[120:123], v[176:179], v[84:87]
	v_mfma_f32_16x16x32_bf16 v[80:83], v[136:139], v[176:179], v[80:83]
	v_mfma_f32_16x16x32_bf16 v[68:71], v[120:123], v[206:209], v[68:71]
	v_mfma_f32_16x16x32_bf16 v[64:67], v[136:139], v[206:209], v[64:67]
	v_mfma_f32_16x16x32_bf16 v[148:151], v[124:127], v[156:159], v[148:151]
	v_mfma_f32_16x16x32_bf16 v[144:147], v[140:143], v[156:159], v[144:147]
	v_mfma_f32_16x16x32_bf16 v[116:119], v[124:127], v[172:175], v[116:119]
	v_mfma_f32_16x16x32_bf16 v[112:115], v[140:143], v[172:175], v[112:115]
	v_mfma_f32_16x16x32_bf16 v[84:87], v[124:127], v[180:183], v[84:87]
	v_mfma_f32_16x16x32_bf16 v[80:83], v[140:143], v[180:183], v[80:83]
	v_mfma_f32_16x16x32_bf16 v[68:71], v[124:127], v[210:213], v[68:71]
	v_mfma_f32_16x16x32_bf16 v[64:67], v[140:143], v[210:213], v[64:67]
	s_setprio 0
	s_barrier
; #define PG8_STAGE(bufoff, gbase, voff) do { _Pragma("unroll") for (int _i = 0; _i < 2; ++_i) \
;         __builtin_amdgcn_global_load_lds((const unsigned*)((const char*)(gbase) + (voff)[_i]), (LAS unsigned*)(lds + (bufoff) + ldsw + _i * 8192), 16, 0, 0); } while (0)
; #define PG8_LDA(dst, b, h) do { _Pragma("unroll") for (int m = 0; m < 4; ++m) _Pragma("unroll") for (int k = 0; k < 2; ++k) dst[m][k] = *(const LAS bf16x8*)(lds + PG8_SA(b, h) + aoff + m * 2048 + k * 1024); } while (0)
; #define PG8_MMA(ai, bj, At, Bt) do { __builtin_amdgcn_s_setprio(1); _Pragma("unroll") for (int m = 0; m < 4; ++m) _Pragma("unroll") for (int n = 0; n < 2; ++n) _Pragma("unroll") for (int k = 0; k < 2; ++k) \
;         acc[ai][bj][m][n] = __builtin_amdgcn_mfma_f32_16x16x32_bf16(Bt[n][k], At[m][k], acc[ai][bj][m][n], 0, 0, 0); __builtin_amdgcn_s_setprio(0); } while (0)
; #define PG8_WAIT_V(n) asm volatile("s_waitcnt vmcnt(" #n ")" ::: "memory")
; #define PG8_WAIT_L(n) asm volatile("s_waitcnt lgkmcnt(" #n ")" ::: "memory")
; #define PG8_BAR __builtin_amdgcn_s_barrier()
; #define PG8_SCHED __builtin_amdgcn_sched_barrier(0)
; template <class Epi, class Sched>
; __device__ __forceinline__ void gemm_phase(LAS unsigned char* lds, const Gemm g, const Sched& S, const Epi& E) {
;     ...
;         for (int t = 0; t < nt; t += 2) {
;             const bool last = (t == nt - 2);
;     ...
;             PG8_LDA(At, 1, 1); PG8_STAGE(PG8_SB(1, 0), b3, voffB); PG8_STAGE(PG8_SB(1, 1), b3 + hstepB, voffB); PG8_STAGE(PG8_SA(1, 0), a3, voffA);
;             PG8_WAIT_V(8); PG8_WAIT_L(0); PG8_BAR; PG8_MMA(1, 0, At, B0); PG8_MMA(1, 1, At, B1); PG8_BAR; PG8_SCHED;
	s_add_i32 s22, s49, s28
	v_lshl_add_u64 v[214:215], v[214:215], 0, s[12:13]
	s_mov_b32 m0, s22
	ds_read_b128 v[152:155], v228 offset:49152
	ds_read_b128 v[156:159], v228 offset:50176
	ds_read_b128 v[168:171], v228 offset:51200
	ds_read_b128 v[172:175], v228 offset:52224
	ds_read_b128 v[176:179], v228 offset:53248
	ds_read_b128 v[180:183], v228 offset:54272
	ds_read_b128 v[206:209], v228 offset:55296
	ds_read_b128 v[210:213], v228 offset:56320
	global_load_lds_dwordx4 v[214:215], off
	s_add_i32 m0, s22, 0x2000
	s_add_u32 s20, s20, 0xc0080
	v_lshl_add_u64 v[214:215], v[216:217], 0, s[12:13]
	s_addc_u32 s21, s21, 0
	s_add_i32 s22, s50, s28
	global_load_lds_dwordx4 v[214:215], off
	v_lshl_add_u64 v[214:215], s[20:21], 0, v[192:193]
	s_mov_b32 m0, s22
	s_nop 0
	global_load_lds_dwordx4 v[214:215], off
	v_lshl_add_u64 v[214:215], s[20:21], 0, v[196:197]
	s_add_i32 m0, s22, 0x2000
	s_nop 0
	global_load_lds_dwordx4 v[214:215], off
	v_lshl_add_u64 v[214:215], v[218:219], 0, s[12:13]
	s_mov_b32 m0, s35
	s_nop 0
	global_load_lds_dwordx4 v[214:215], off
	v_lshl_add_u64 v[214:215], v[220:221], 0, s[12:13]
	s_mov_b32 m0, s36
	s_nop 0
	global_load_lds_dwordx4 v[214:215], off
	s_waitcnt vmcnt(8)
	s_waitcnt lgkmcnt(0)
	s_barrier
	s_setprio 1
	s_waitcnt lgkmcnt(0)
	v_mfma_f32_16x16x32_bf16 v[60:63], v[88:91], v[152:155], v[60:63]
	v_mfma_f32_16x16x32_bf16 v[56:59], v[104:107], v[152:155], v[56:59]
	s_add_i32 s48, s48, 2
	v_mfma_f32_16x16x32_bf16 v[44:47], v[88:91], v[168:171], v[44:47]
	s_add_u32 s18, s18, 0x100
	v_mfma_f32_16x16x32_bf16 v[40:43], v[104:107], v[168:171], v[40:43]
	s_addc_u32 s19, s19, 0
	v_mfma_f32_16x16x32_bf16 v[28:31], v[88:91], v[176:179], v[28:31]
	s_add_u32 s46, s46, 0x100
	v_mfma_f32_16x16x32_bf16 v[24:27], v[104:107], v[176:179], v[24:27]
	s_addc_u32 s47, s47, 0
	v_mfma_f32_16x16x32_bf16 v[12:15], v[88:91], v[206:209], v[12:15]
	s_cmp_gt_u32 s48, 29
	v_mfma_f32_16x16x32_bf16 v[8:11], v[104:107], v[206:209], v[8:11]
	v_mfma_f32_16x16x32_bf16 v[60:63], v[92:95], v[156:159], v[60:63]
	v_mfma_f32_16x16x32_bf16 v[56:59], v[108:111], v[156:159], v[56:59]
	v_mfma_f32_16x16x32_bf16 v[44:47], v[92:95], v[172:175], v[44:47]
	v_mfma_f32_16x16x32_bf16 v[40:43], v[108:111], v[172:175], v[40:43]
	v_mfma_f32_16x16x32_bf16 v[28:31], v[92:95], v[180:183], v[28:31]
	v_mfma_f32_16x16x32_bf16 v[24:27], v[108:111], v[180:183], v[24:27]
	v_mfma_f32_16x16x32_bf16 v[12:15], v[92:95], v[210:213], v[12:15]
	v_mfma_f32_16x16x32_bf16 v[8:11], v[108:111], v[210:213], v[8:11]
	s_setprio 0
	s_setprio 1
	v_mfma_f32_16x16x32_bf16 v[52:55], v[120:123], v[152:155], v[52:55]
	v_mfma_f32_16x16x32_bf16 v[48:51], v[136:139], v[152:155], v[48:51]
	v_mfma_f32_16x16x32_bf16 v[36:39], v[120:123], v[168:171], v[36:39]
	v_mfma_f32_16x16x32_bf16 v[32:35], v[136:139], v[168:171], v[32:35]
	v_mfma_f32_16x16x32_bf16 v[20:23], v[120:123], v[176:179], v[20:23]
	v_mfma_f32_16x16x32_bf16 v[16:19], v[136:139], v[176:179], v[16:19]
	v_mfma_f32_16x16x32_bf16 v[4:7], v[120:123], v[206:209], v[4:7]
	v_mfma_f32_16x16x32_bf16 v[0:3], v[136:139], v[206:209], v[0:3]
	v_mfma_f32_16x16x32_bf16 v[52:55], v[124:127], v[156:159], v[52:55]
	v_mfma_f32_16x16x32_bf16 v[48:51], v[140:143], v[156:159], v[48:51]
	v_mfma_f32_16x16x32_bf16 v[36:39], v[124:127], v[172:175], v[36:39]
	v_mfma_f32_16x16x32_bf16 v[32:35], v[140:143], v[172:175], v[32:35]
	v_mfma_f32_16x16x32_bf16 v[20:23], v[124:127], v[180:183], v[20:23]
	v_mfma_f32_16x16x32_bf16 v[16:19], v[140:143], v[180:183], v[16:19]
	v_mfma_f32_16x16x32_bf16 v[4:7], v[124:127], v[210:213], v[4:7]
	v_mfma_f32_16x16x32_bf16 v[0:3], v[140:143], v[210:213], v[0:3]
	s_setprio 0
	s_barrier
	s_cbranch_scc0 .LBB0_697
	s_and_b64 vcc, exec, s[14:15]
	s_cbranch_vccz .LBB0_700
	s_barrier

; #define PG8_STAGE(bufoff, gbase, voff) do { _Pragma("unroll") for (int _i = 0; _i < 2; ++_i) \
;         __builtin_amdgcn_global_load_lds((const unsigned*)((const char*)(gbase) + (voff)[_i]), (LAS unsigned*)(lds + (bufoff) + ldsw + _i * 8192), 16, 0, 0); } while (0)
; #define PG8_LDA(dst, b, h) do { _Pragma("unroll") for (int m = 0; m < 4; ++m) _Pragma("unroll") for (int k = 0; k < 2; ++k) dst[m][k] = *(const LAS bf16x8*)(lds + PG8_SA(b, h) + aoff + m * 2048 + k * 1024); } while (0)
; #define PG8_LDB(dst, b, h) do { _Pragma("unroll") for (int n = 0; n < 2; ++n) _Pragma("unroll") for (int k = 0; k < 2; ++k) dst[n][k] = *(const LAS bf16x8*)(lds + PG8_SB(b, h) + boff + n * 2048 + k * 1024); } while (0)
; #define PG8_MMA(ai, bj, At, Bt) do { __builtin_amdgcn_s_setprio(1); _Pragma("unroll") for (int m = 0; m < 4; ++m) _Pragma("unroll") for (int n = 0; n < 2; ++n) _Pragma("unroll") for (int k = 0; k < 2; ++k) \
;         acc[ai][bj][m][n] = __builtin_amdgcn_mfma_f32_16x16x32_bf16(Bt[n][k], At[m][k], acc[ai][bj][m][n], 0, 0, 0); __builtin_amdgcn_s_setprio(0); } while (0)
; #define PG8_WAIT_V(n) asm volatile("s_waitcnt vmcnt(" #n ")" ::: "memory")
; #define PG8_WAIT_L(n) asm volatile("s_waitcnt lgkmcnt(" #n ")" ::: "memory")
; #define PG8_BAR __builtin_amdgcn_s_barrier()
; #define PG8_SCHED __builtin_amdgcn_sched_barrier(0)
; template <class Epi, class Sched>
; __device__ __forceinline__ void gemm_phase(LAS unsigned char* lds, const Gemm g, const Sched& S, const Epi& E) {
;     ...
;         for (int t = 0; t < nt; t += 2) {
;             const bool last = (t == nt - 2);
;             const char* a1 = cA + (size_t)(t + 1) * kstep;
;             const char* a2 = last ? nA : cA + (size_t)(t + 2) * kstep; const char* b2 = last ? nB : cB + (size_t)(t + 2) * kstep;
;             const char* a3 = a2 + kstep; const char* b3 = b2 + kstep;
;             PG8_LDB(B0, 0, 0); PG8_LDB(B1, 0, 1); PG8_SCHED; PG8_LDA(At, 0, 0); PG8_STAGE(PG8_SA(1, 1), a1 + hstepA, voffA);
;             PG8_WAIT_V(8); PG8_WAIT_L(0); PG8_BAR; PG8_MMA(0, 0, At, B0); PG8_MMA(0, 1, At, B1); PG8_BAR; PG8_SCHED;
;             PG8_LDA(At, 0, 1); PG8_STAGE(PG8_SB(0, 0), b2, voffB); PG8_STAGE(PG8_SB(0, 1), b2 + hstepB, voffB); PG8_STAGE(PG8_SA(0, 0), a2, voffA);
.LBB0_787:
	ds_read_b128 v[128:131], v212
	ds_read_b128 v[132:135], v212 offset:1024
	ds_read_b128 v[136:139], v212 offset:2048
	ds_read_b128 v[140:143], v212 offset:3072
	ds_read_b128 v[144:147], v213
	ds_read_b128 v[148:151], v213 offset:1024
	ds_read_b128 v[152:155], v213 offset:2048
	ds_read_b128 v[156:159], v213 offset:3072
	s_add_u32 s34, s30, 0x100
	s_addc_u32 s35, s31, 0
	s_cmp_eq_u32 s60, 28
	s_cselect_b32 s39, s23, s35
	s_cselect_b32 s38, s29, s34
	s_cselect_b32 s37, s21, s59
	s_cselect_b32 s36, s57, s58
	v_lshl_add_u64 v[220:221], s[30:31], 0, v[190:191]
	s_add_i32 m0, s33, 0xc000
	ds_read_b128 v[160:163], v214
	ds_read_b128 v[164:167], v214 offset:1024
	ds_read_b128 v[168:171], v214 offset:2048
	ds_read_b128 v[172:175], v214 offset:3072
	ds_read_b128 v[198:201], v214 offset:4096
	ds_read_b128 v[202:205], v214 offset:5120
	ds_read_b128 v[206:209], v214 offset:6144
	ds_read_b128 v[216:219], v214 offset:7168
	global_load_lds_dwordx4 v[220:221], off
	v_lshl_add_u64 v[220:221], s[30:31], 0, v[192:193]
	s_add_i32 m0, s33, 0xe000
	s_nop 0
	global_load_lds_dwordx4 v[220:221], off
	s_waitcnt vmcnt(8)
	s_waitcnt lgkmcnt(0)
	s_barrier
	s_setprio 1
	s_waitcnt lgkmcnt(0)
	v_mfma_f32_16x16x32_bf16 v[124:127], v[128:131], v[160:163], v[124:127]
	v_mfma_f32_16x16x32_bf16 v[120:123], v[136:139], v[160:163], v[120:123]
	v_mfma_f32_16x16x32_bf16 v[108:111], v[128:131], v[168:171], v[108:111]
	v_mfma_f32_16x16x32_bf16 v[104:107], v[136:139], v[168:171], v[104:107]
	v_mfma_f32_16x16x32_bf16 v[92:95], v[128:131], v[198:201], v[92:95]
	v_mfma_f32_16x16x32_bf16 v[88:91], v[136:139], v[198:201], v[88:91]
	v_mfma_f32_16x16x32_bf16 v[76:79], v[128:131], v[206:209], v[76:79]
	v_mfma_f32_16x16x32_bf16 v[72:75], v[136:139], v[206:209], v[72:75]
	v_mfma_f32_16x16x32_bf16 v[124:127], v[132:135], v[164:167], v[124:127]
	v_mfma_f32_16x16x32_bf16 v[120:123], v[140:143], v[164:167], v[120:123]
	v_mfma_f32_16x16x32_bf16 v[108:111], v[132:135], v[172:175], v[108:111]
	v_mfma_f32_16x16x32_bf16 v[104:107], v[140:143], v[172:175], v[104:107]
	v_mfma_f32_16x16x32_bf16 v[92:95], v[132:135], v[202:205], v[92:95]
	v_mfma_f32_16x16x32_bf16 v[88:91], v[140:143], v[202:205], v[88:91]
	v_mfma_f32_16x16x32_bf16 v[76:79], v[132:135], v[216:219], v[76:79]
	v_mfma_f32_16x16x32_bf16 v[72:75], v[140:143], v[216:219], v[72:75]
	s_setprio 0
	s_setprio 1
	v_mfma_f32_16x16x32_bf16 v[116:119], v[144:147], v[160:163], v[116:119]
	v_mfma_f32_16x16x32_bf16 v[112:115], v[152:155], v[160:163], v[112:115]
	v_mfma_f32_16x16x32_bf16 v[100:103], v[144:147], v[168:171], v[100:103]
	v_mfma_f32_16x16x32_bf16 v[96:99], v[152:155], v[168:171], v[96:99]
	v_mfma_f32_16x16x32_bf16 v[84:87], v[144:147], v[198:201], v[84:87]
	v_mfma_f32_16x16x32_bf16 v[80:83], v[152:155], v[198:201], v[80:83]
	v_mfma_f32_16x16x32_bf16 v[68:71], v[144:147], v[206:209], v[68:71]
	v_mfma_f32_16x16x32_bf16 v[64:67], v[152:155], v[206:209], v[64:67]
	v_mfma_f32_16x16x32_bf16 v[116:119], v[148:151], v[164:167], v[116:119]
	v_mfma_f32_16x16x32_bf16 v[112:115], v[156:159], v[164:167], v[112:115]
	v_mfma_f32_16x16x32_bf16 v[100:103], v[148:151], v[172:175], v[100:103]
	v_mfma_f32_16x16x32_bf16 v[96:99], v[156:159], v[172:175], v[96:99]
	v_mfma_f32_16x16x32_bf16 v[84:87], v[148:151], v[202:205], v[84:87]
	v_mfma_f32_16x16x32_bf16 v[80:83], v[156:159], v[202:205], v[80:83]
	v_mfma_f32_16x16x32_bf16 v[68:71], v[148:151], v[216:219], v[68:71]
	v_mfma_f32_16x16x32_bf16 v[64:67], v[156:159], v[216:219], v[64:67]
	s_setprio 0
	s_barrier
	s_add_i32 s30, s50, s3
	v_lshl_add_u64 v[220:221], s[36:37], 0, v[178:179]
	s_mov_b32 m0, s30
	ds_read_b128 v[160:163], v214 offset:16384
	ds_read_b128 v[164:167], v214 offset:17408
	ds_read_b128 v[168:171], v214 offset:18432
	ds_read_b128 v[172:175], v214 offset:19456
	ds_read_b128 v[198:201], v214 offset:20480
	ds_read_b128 v[202:205], v214 offset:21504
	ds_read_b128 v[206:209], v214 offset:22528
	ds_read_b128 v[216:219], v214 offset:23552
	global_load_lds_dwordx4 v[220:221], off
	s_add_i32 m0, s30, 0x2000
	s_add_u32 s30, s36, 0x80000
	v_lshl_add_u64 v[224:225], s[36:37], 0, v[182:183]
	s_addc_u32 s31, s37, 0
	s_add_i32 s61, s51, s3
	global_load_lds_dwordx4 v[224:225], off
	v_lshl_add_u64 v[226:227], s[30:31], 0, v[178:179]
	s_mov_b32 m0, s61
	v_lshl_add_u64 v[228:229], s[38:39], 0, v[180:181]
	global_load_lds_dwordx4 v[226:227], off
	v_lshl_add_u64 v[226:227], s[30:31], 0, v[182:183]
	s_add_i32 m0, s61, 0x2000
	s_nop 0
	global_load_lds_dwordx4 v[226:227], off
	v_lshl_add_u64 v[226:227], s[38:39], 0, v[176:177]
	s_mov_b32 m0, s33
	s_nop 0
	global_load_lds_dwordx4 v[226:227], off
	s_mov_b32 m0, s40
	s_nop 0
	global_load_lds_dwordx4 v[228:229], off
	s_waitcnt vmcnt(8)
	s_waitcnt lgkmcnt(0)
	s_barrier
; #define PG8_STAGE(bufoff, gbase, voff) do { _Pragma("unroll") for (int _i = 0; _i < 2; ++_i) \
;         __builtin_amdgcn_global_load_lds((const unsigned*)((const char*)(gbase) + (voff)[_i]), (LAS unsigned*)(lds + (bufoff) + ldsw + _i * 8192), 16, 0, 0); } while (0)
; #define PG8_LDA(dst, b, h) do { _Pragma("unroll") for (int m = 0; m < 4; ++m) _Pragma("unroll") for (int k = 0; k < 2; ++k) dst[m][k] = *(const LAS bf16x8*)(lds + PG8_SA(b, h) + aoff + m * 2048 + k * 1024); } while (0)
; #define PG8_LDB(dst, b, h) do { _Pragma("unroll") for (int n = 0; n < 2; ++n) _Pragma("unroll") for (int k = 0; k < 2; ++k) dst[n][k] = *(const LAS bf16x8*)(lds + PG8_SB(b, h) + boff + n * 2048 + k * 1024); } while (0)
; #define PG8_MMA(ai, bj, At, Bt) do { __builtin_amdgcn_s_setprio(1); _Pragma("unroll") for (int m = 0; m < 4; ++m) _Pragma("unroll") for (int n = 0; n < 2; ++n) _Pragma("unroll") for (int k = 0; k < 2; ++k) \
;         acc[ai][bj][m][n] = __builtin_amdgcn_mfma_f32_16x16x32_bf16(Bt[n][k], At[m][k], acc[ai][bj][m][n], 0, 0, 0); __builtin_amdgcn_s_setprio(0); } while (0)
; #define PG8_WAIT_V(n) asm volatile("s_waitcnt vmcnt(" #n ")" ::: "memory")
; #define PG8_WAIT_L(n) asm volatile("s_waitcnt lgkmcnt(" #n ")" ::: "memory")
; #define PG8_BAR __builtin_amdgcn_s_barrier()
; #define PG8_SCHED __builtin_amdgcn_sched_barrier(0)
; template <class Epi, class Sched>
; __device__ __forceinline__ void gemm_phase(LAS unsigned char* lds, const Gemm g, const Sched& S, const Epi& E) {
;     ...
;             PG8_WAIT_V(8); PG8_WAIT_L(0); PG8_BAR; PG8_MMA(1, 0, At, B0); PG8_MMA(1, 1, At, B1); PG8_BAR; PG8_SCHED;
;             PG8_LDB(B0, 1, 0); PG8_LDB(B1, 1, 1); PG8_SCHED; PG8_LDA(At, 1, 0); PG8_STAGE(PG8_SA(0, 1), a2 + hstepA, voffA);
;             PG8_WAIT_V(8); PG8_WAIT_L(0); PG8_BAR; PG8_MMA(0, 0, At, B0); PG8_MMA(0, 1, At, B1); PG8_BAR; PG8_SCHED;
	s_setprio 1
	s_waitcnt lgkmcnt(0)
	v_mfma_f32_16x16x32_bf16 v[60:63], v[128:131], v[160:163], v[60:63]
	v_mfma_f32_16x16x32_bf16 v[56:59], v[136:139], v[160:163], v[56:59]
	v_mfma_f32_16x16x32_bf16 v[44:47], v[128:131], v[168:171], v[44:47]
	v_mfma_f32_16x16x32_bf16 v[40:43], v[136:139], v[168:171], v[40:43]
	v_mfma_f32_16x16x32_bf16 v[28:31], v[128:131], v[198:201], v[28:31]
	v_mfma_f32_16x16x32_bf16 v[24:27], v[136:139], v[198:201], v[24:27]
	v_mfma_f32_16x16x32_bf16 v[12:15], v[128:131], v[206:209], v[12:15]
	v_mfma_f32_16x16x32_bf16 v[8:11], v[136:139], v[206:209], v[8:11]
	v_mfma_f32_16x16x32_bf16 v[60:63], v[132:135], v[164:167], v[60:63]
	v_mfma_f32_16x16x32_bf16 v[56:59], v[140:143], v[164:167], v[56:59]
	v_mfma_f32_16x16x32_bf16 v[44:47], v[132:135], v[172:175], v[44:47]
	v_mfma_f32_16x16x32_bf16 v[40:43], v[140:143], v[172:175], v[40:43]
	v_mfma_f32_16x16x32_bf16 v[28:31], v[132:135], v[202:205], v[28:31]
	v_mfma_f32_16x16x32_bf16 v[24:27], v[140:143], v[202:205], v[24:27]
	v_mfma_f32_16x16x32_bf16 v[12:15], v[132:135], v[216:219], v[12:15]
	v_mfma_f32_16x16x32_bf16 v[8:11], v[140:143], v[216:219], v[8:11]
	s_setprio 0
	s_setprio 1
	v_mfma_f32_16x16x32_bf16 v[52:55], v[144:147], v[160:163], v[52:55]
	v_mfma_f32_16x16x32_bf16 v[48:51], v[152:155], v[160:163], v[48:51]
	v_mfma_f32_16x16x32_bf16 v[36:39], v[144:147], v[168:171], v[36:39]
	v_mfma_f32_16x16x32_bf16 v[32:35], v[152:155], v[168:171], v[32:35]
	v_mfma_f32_16x16x32_bf16 v[20:23], v[144:147], v[198:201], v[20:23]
	v_mfma_f32_16x16x32_bf16 v[16:19], v[152:155], v[198:201], v[16:19]
	v_mfma_f32_16x16x32_bf16 v[4:7], v[144:147], v[206:209], v[4:7]
	v_mfma_f32_16x16x32_bf16 v[0:3], v[152:155], v[206:209], v[0:3]
	v_mfma_f32_16x16x32_bf16 v[52:55], v[148:151], v[164:167], v[52:55]
	v_mfma_f32_16x16x32_bf16 v[48:51], v[156:159], v[164:167], v[48:51]
	v_mfma_f32_16x16x32_bf16 v[36:39], v[148:151], v[172:175], v[36:39]
	v_mfma_f32_16x16x32_bf16 v[32:35], v[156:159], v[172:175], v[32:35]
	v_mfma_f32_16x16x32_bf16 v[20:23], v[148:151], v[202:205], v[20:23]
	v_mfma_f32_16x16x32_bf16 v[16:19], v[156:159], v[202:205], v[16:19]
	v_mfma_f32_16x16x32_bf16 v[4:7], v[148:151], v[216:219], v[4:7]
	v_mfma_f32_16x16x32_bf16 v[0:3], v[156:159], v[216:219], v[0:3]
	s_setprio 0
	s_barrier
	s_add_i32 s61, 0, 0x18000
	s_add_i32 s62, 0, 0x1c000
	v_add_u32_e32 v140, s61, v210
	v_add_u32_e32 v156, s62, v210
	ds_read_b128 v[128:131], v140
	ds_read_b128 v[132:135], v140 offset:1024
	ds_read_b128 v[136:139], v140 offset:2048
	ds_read_b128 v[140:143], v140 offset:3072
	ds_read_b128 v[144:147], v156
	ds_read_b128 v[148:151], v156 offset:1024
	ds_read_b128 v[152:155], v156 offset:2048
	ds_read_b128 v[156:159], v156 offset:3072
	s_add_u32 s30, s38, 0x80000
	s_addc_u32 s31, s39, 0
	s_mov_b32 m0, s41
	v_lshl_add_u64 v[230:231], s[30:31], 0, v[176:177]
	ds_read_b128 v[160:163], v214 offset:32768
	ds_read_b128 v[164:167], v214 offset:33792
	ds_read_b128 v[168:171], v214 offset:34816
	ds_read_b128 v[172:175], v214 offset:35840
	ds_read_b128 v[198:201], v214 offset:36864
	ds_read_b128 v[202:205], v214 offset:37888
	ds_read_b128 v[206:209], v214 offset:38912
	ds_read_b128 v[216:219], v214 offset:39936
	global_load_lds_dwordx4 v[230:231], off
	v_lshl_add_u64 v[230:231], s[30:31], 0, v[180:181]
	s_mov_b32 m0, s42
	s_nop 0
	global_load_lds_dwordx4 v[230:231], off
	s_waitcnt vmcnt(8)
	s_waitcnt lgkmcnt(0)
	s_barrier
	s_setprio 1
	s_waitcnt lgkmcnt(0)
	v_mfma_f32_16x16x32_bf16 v[124:127], v[128:131], v[160:163], v[124:127]
	v_mfma_f32_16x16x32_bf16 v[120:123], v[136:139], v[160:163], v[120:123]
	v_mfma_f32_16x16x32_bf16 v[108:111], v[128:131], v[168:171], v[108:111]
	v_mfma_f32_16x16x32_bf16 v[104:107], v[136:139], v[168:171], v[104:107]
	v_mfma_f32_16x16x32_bf16 v[92:95], v[128:131], v[198:201], v[92:95]
	v_mfma_f32_16x16x32_bf16 v[88:91], v[136:139], v[198:201], v[88:91]
	v_mfma_f32_16x16x32_bf16 v[76:79], v[128:131], v[206:209], v[76:79]
	v_mfma_f32_16x16x32_bf16 v[72:75], v[136:139], v[206:209], v[72:75]
	v_mfma_f32_16x16x32_bf16 v[124:127], v[132:135], v[164:167], v[124:127]
	v_mfma_f32_16x16x32_bf16 v[120:123], v[140:143], v[164:167], v[120:123]
	v_mfma_f32_16x16x32_bf16 v[108:111], v[132:135], v[172:175], v[108:111]
	v_mfma_f32_16x16x32_bf16 v[104:107], v[140:143], v[172:175], v[104:107]
	v_mfma_f32_16x16x32_bf16 v[92:95], v[132:135], v[202:205], v[92:95]
	v_mfma_f32_16x16x32_bf16 v[88:91], v[140:143], v[202:205], v[88:91]
	v_mfma_f32_16x16x32_bf16 v[76:79], v[132:135], v[216:219], v[76:79]
	v_mfma_f32_16x16x32_bf16 v[72:75], v[140:143], v[216:219], v[72:75]
	s_setprio 0
	s_setprio 1
	v_mfma_f32_16x16x32_bf16 v[116:119], v[144:147], v[160:163], v[116:119]
	v_mfma_f32_16x16x32_bf16 v[112:115], v[152:155], v[160:163], v[112:115]
	v_mfma_f32_16x16x32_bf16 v[100:103], v[144:147], v[168:171], v[100:103]
	v_mfma_f32_16x16x32_bf16 v[96:99], v[152:155], v[168:171], v[96:99]
	v_mfma_f32_16x16x32_bf16 v[84:87], v[144:147], v[198:201], v[84:87]
	v_mfma_f32_16x16x32_bf16 v[80:83], v[152:155], v[198:201], v[80:83]
	v_mfma_f32_16x16x32_bf16 v[68:71], v[144:147], v[206:209], v[68:71]
	v_mfma_f32_16x16x32_bf16 v[64:67], v[152:155], v[206:209], v[64:67]
	v_mfma_f32_16x16x32_bf16 v[116:119], v[148:151], v[164:167], v[116:119]
	v_mfma_f32_16x16x32_bf16 v[112:115], v[156:159], v[164:167], v[112:115]
	v_mfma_f32_16x16x32_bf16 v[100:103], v[148:151], v[172:175], v[100:103]
	v_mfma_f32_16x16x32_bf16 v[96:99], v[156:159], v[172:175], v[96:99]
	v_mfma_f32_16x16x32_bf16 v[84:87], v[148:151], v[202:205], v[84:87]
	v_mfma_f32_16x16x32_bf16 v[80:83], v[156:159], v[202:205], v[80:83]
	v_mfma_f32_16x16x32_bf16 v[68:71], v[148:151], v[216:219], v[68:71]
	v_mfma_f32_16x16x32_bf16 v[64:67], v[156:159], v[216:219], v[64:67]
	s_setprio 0
	s_barrier
; #define PG8_STAGE(bufoff, gbase, voff) do { _Pragma("unroll") for (int _i = 0; _i < 2; ++_i) \
;         __builtin_amdgcn_global_load_lds((const unsigned*)((const char*)(gbase) + (voff)[_i]), (LAS unsigned*)(lds + (bufoff) + ldsw + _i * 8192), 16, 0, 0); } while (0)
; #define PG8_LDA(dst, b, h) do { _Pragma("unroll") for (int m = 0; m < 4; ++m) _Pragma("unroll") for (int k = 0; k < 2; ++k) dst[m][k] = *(const LAS bf16x8*)(lds + PG8_SA(b, h) + aoff + m * 2048 + k * 1024); } while (0)
; #define PG8_MMA(ai, bj, At, Bt) do { __builtin_amdgcn_s_setprio(1); _Pragma("unroll") for (int m = 0; m < 4; ++m) _Pragma("unroll") for (int n = 0; n < 2; ++n) _Pragma("unroll") for (int k = 0; k < 2; ++k) \
;         acc[ai][bj][m][n] = __builtin_amdgcn_mfma_f32_16x16x32_bf16(Bt[n][k], At[m][k], acc[ai][bj][m][n], 0, 0, 0); __builtin_amdgcn_s_setprio(0); } while (0)
; #define PG8_WAIT_V(n) asm volatile("s_waitcnt vmcnt(" #n ")" ::: "memory")
; #define PG8_WAIT_L(n) asm volatile("s_waitcnt lgkmcnt(" #n ")" ::: "memory")
; #define PG8_BAR __builtin_amdgcn_s_barrier()
; #define PG8_SCHED __builtin_amdgcn_sched_barrier(0)
; template <class Epi, class Sched>
; __device__ __forceinline__ void gemm_phase(LAS unsigned char* lds, const Gemm g, const Sched& S, const Epi& E) {
;     ...
;         for (int t = 0; t < nt; t += 2) {
;             const bool last = (t == nt - 2);
;     ...
;             PG8_LDA(At, 1, 1); PG8_STAGE(PG8_SB(1, 0), b3, voffB); PG8_STAGE(PG8_SB(1, 1), b3 + hstepB, voffB); PG8_STAGE(PG8_SA(1, 0), a3, voffA);
;             PG8_WAIT_V(8); PG8_WAIT_L(0); PG8_BAR; PG8_MMA(1, 0, At, B0); PG8_MMA(1, 1, At, B1); PG8_BAR; PG8_SCHED;
	s_add_i32 s30, s61, s3
	v_lshl_add_u64 v[220:221], v[220:221], 0, s[10:11]
	s_mov_b32 m0, s30
	ds_read_b128 v[160:163], v214 offset:49152
	ds_read_b128 v[164:167], v214 offset:50176
	ds_read_b128 v[168:171], v214 offset:51200
	ds_read_b128 v[172:175], v214 offset:52224
	ds_read_b128 v[198:201], v214 offset:53248
	ds_read_b128 v[202:205], v214 offset:54272
	ds_read_b128 v[206:209], v214 offset:55296
	ds_read_b128 v[216:219], v214 offset:56320
	global_load_lds_dwordx4 v[220:221], off
	s_add_i32 m0, s30, 0x2000
	s_add_u32 s30, s36, 0x80080
	v_lshl_add_u64 v[220:221], v[224:225], 0, s[10:11]
	s_addc_u32 s31, s37, 0
	s_add_i32 s36, s62, s3
	global_load_lds_dwordx4 v[220:221], off
	v_lshl_add_u64 v[220:221], s[30:31], 0, v[178:179]
	s_mov_b32 m0, s36
	s_nop 0
	global_load_lds_dwordx4 v[220:221], off
	v_lshl_add_u64 v[220:221], s[30:31], 0, v[182:183]
	s_add_i32 m0, s36, 0x2000
	s_nop 0
	global_load_lds_dwordx4 v[220:221], off
	v_lshl_add_u64 v[220:221], v[226:227], 0, s[10:11]
	s_mov_b32 m0, s45
	s_nop 0
	global_load_lds_dwordx4 v[220:221], off
	v_lshl_add_u64 v[220:221], v[228:229], 0, s[10:11]
	s_mov_b32 m0, s46
	s_nop 0
	global_load_lds_dwordx4 v[220:221], off
	s_waitcnt vmcnt(8)
	s_waitcnt lgkmcnt(0)
	s_barrier
	s_setprio 1
	s_waitcnt lgkmcnt(0)
	v_mfma_f32_16x16x32_bf16 v[60:63], v[128:131], v[160:163], v[60:63]
	v_mfma_f32_16x16x32_bf16 v[56:59], v[136:139], v[160:163], v[56:59]
	s_add_i32 s60, s60, 2
	v_mfma_f32_16x16x32_bf16 v[44:47], v[128:131], v[168:171], v[44:47]
	s_add_u32 s58, s58, 0x100
	v_mfma_f32_16x16x32_bf16 v[40:43], v[136:139], v[168:171], v[40:43]
	s_addc_u32 s59, s59, 0
	v_mfma_f32_16x16x32_bf16 v[28:31], v[128:131], v[198:201], v[28:31]
	s_mov_b64 s[30:31], s[34:35]
	v_mfma_f32_16x16x32_bf16 v[24:27], v[136:139], v[198:201], v[24:27]
	s_cmp_gt_u32 s60, 29
	v_mfma_f32_16x16x32_bf16 v[12:15], v[128:131], v[206:209], v[12:15]
	v_mfma_f32_16x16x32_bf16 v[8:11], v[136:139], v[206:209], v[8:11]
	v_mfma_f32_16x16x32_bf16 v[60:63], v[132:135], v[164:167], v[60:63]
	v_mfma_f32_16x16x32_bf16 v[56:59], v[140:143], v[164:167], v[56:59]
	v_mfma_f32_16x16x32_bf16 v[44:47], v[132:135], v[172:175], v[44:47]
	v_mfma_f32_16x16x32_bf16 v[40:43], v[140:143], v[172:175], v[40:43]
	v_mfma_f32_16x16x32_bf16 v[28:31], v[132:135], v[202:205], v[28:31]
	v_mfma_f32_16x16x32_bf16 v[24:27], v[140:143], v[202:205], v[24:27]
	v_mfma_f32_16x16x32_bf16 v[12:15], v[132:135], v[216:219], v[12:15]
	v_mfma_f32_16x16x32_bf16 v[8:11], v[140:143], v[216:219], v[8:11]
	s_setprio 0
	s_setprio 1
	v_mfma_f32_16x16x32_bf16 v[52:55], v[144:147], v[160:163], v[52:55]
	v_mfma_f32_16x16x32_bf16 v[48:51], v[152:155], v[160:163], v[48:51]
	v_mfma_f32_16x16x32_bf16 v[36:39], v[144:147], v[168:171], v[36:39]
	v_mfma_f32_16x16x32_bf16 v[32:35], v[152:155], v[168:171], v[32:35]
	v_mfma_f32_16x16x32_bf16 v[20:23], v[144:147], v[198:201], v[20:23]
	v_mfma_f32_16x16x32_bf16 v[16:19], v[152:155], v[198:201], v[16:19]
	v_mfma_f32_16x16x32_bf16 v[4:7], v[144:147], v[206:209], v[4:7]
	v_mfma_f32_16x16x32_bf16 v[0:3], v[152:155], v[206:209], v[0:3]
	v_mfma_f32_16x16x32_bf16 v[52:55], v[148:151], v[164:167], v[52:55]
	v_mfma_f32_16x16x32_bf16 v[48:51], v[156:159], v[164:167], v[48:51]
	v_mfma_f32_16x16x32_bf16 v[36:39], v[148:151], v[172:175], v[36:39]
	v_mfma_f32_16x16x32_bf16 v[32:35], v[156:159], v[172:175], v[32:35]
	v_mfma_f32_16x16x32_bf16 v[20:23], v[148:151], v[202:205], v[20:23]
	v_mfma_f32_16x16x32_bf16 v[16:19], v[156:159], v[202:205], v[16:19]
	v_mfma_f32_16x16x32_bf16 v[4:7], v[148:151], v[216:219], v[4:7]
	v_mfma_f32_16x16x32_bf16 v[0:3], v[156:159], v[216:219], v[0:3]
	s_setprio 0
	s_barrier
	s_cbranch_scc0 .LBB0_787
	s_and_b64 vcc, exec, s[18:19]
	s_cbranch_vccz .LBB0_790
	s_barrier

; #define PG8_STAGE(bufoff, gbase, voff) do { _Pragma("unroll") for (int _i = 0; _i < 2; ++_i) \
;         __builtin_amdgcn_global_load_lds((const unsigned*)((const char*)(gbase) + (voff)[_i]), (LAS unsigned*)(lds + (bufoff) + ldsw + _i * 8192), 16, 0, 0); } while (0)
; #define PG8_LDA(dst, b, h) do { _Pragma("unroll") for (int m = 0; m < 4; ++m) _Pragma("unroll") for (int k = 0; k < 2; ++k) dst[m][k] = *(const LAS bf16x8*)(lds + PG8_SA(b, h) + aoff + m * 2048 + k * 1024); } while (0)
; #define PG8_LDB(dst, b, h) do { _Pragma("unroll") for (int n = 0; n < 2; ++n) _Pragma("unroll") for (int k = 0; k < 2; ++k) dst[n][k] = *(const LAS bf16x8*)(lds + PG8_SB(b, h) + boff + n * 2048 + k * 1024); } while (0)
; #define PG8_MMA(ai, bj, At, Bt) do { __builtin_amdgcn_s_setprio(1); _Pragma("unroll") for (int m = 0; m < 4; ++m) _Pragma("unroll") for (int n = 0; n < 2; ++n) _Pragma("unroll") for (int k = 0; k < 2; ++k) \
;         acc[ai][bj][m][n] = __builtin_amdgcn_mfma_f32_16x16x32_bf16(Bt[n][k], At[m][k], acc[ai][bj][m][n], 0, 0, 0); __builtin_amdgcn_s_setprio(0); } while (0)
; #define PG8_WAIT_V(n) asm volatile("s_waitcnt vmcnt(" #n ")" ::: "memory")
; #define PG8_WAIT_L(n) asm volatile("s_waitcnt lgkmcnt(" #n ")" ::: "memory")
; #define PG8_BAR __builtin_amdgcn_s_barrier()
; #define PG8_SCHED __builtin_amdgcn_sched_barrier(0)
; template <class Epi, class Sched>
; __device__ __forceinline__ void gemm_phase(LAS unsigned char* lds, const Gemm g, const Sched& S, const Epi& E) {
;     ...
;         for (int t = 0; t < nt; t += 2) {
;             const bool last = (t == nt - 2);
;             const char* a1 = cA + (size_t)(t + 1) * kstep;
;             const char* a2 = last ? nA : cA + (size_t)(t + 2) * kstep; const char* b2 = last ? nB : cB + (size_t)(t + 2) * kstep;
;             const char* a3 = a2 + kstep; const char* b3 = b2 + kstep;
;             PG8_LDB(B0, 0, 0); PG8_LDB(B1, 0, 1); PG8_SCHED; PG8_LDA(At, 0, 0); PG8_STAGE(PG8_SA(1, 1), a1 + hstepA, voffA);
;             PG8_WAIT_V(8); PG8_WAIT_L(0); PG8_BAR; PG8_MMA(0, 0, At, B0); PG8_MMA(0, 1, At, B1); PG8_BAR; PG8_SCHED;
;             PG8_LDA(At, 0, 1); PG8_STAGE(PG8_SB(0, 0), b2, voffB); PG8_STAGE(PG8_SB(0, 1), b2 + hstepB, voffB); PG8_STAGE(PG8_SA(0, 0), a2, voffA);
.LBB0_933:
	ds_read_b128 v[144:147], v155
	ds_read_b128 v[148:151], v155 offset:1024
	ds_read_b128 v[158:161], v155 offset:2048
	ds_read_b128 v[162:165], v155 offset:3072
	ds_read_b128 v[166:169], v156
	ds_read_b128 v[170:173], v156 offset:1024
	ds_read_b128 v[174:177], v156 offset:2048
	ds_read_b128 v[178:181], v156 offset:3072
	s_add_u32 s36, s34, 0xfff80080
	s_addc_u32 s37, s35, -1
	s_cmp_eq_u32 s60, 28
	s_cselect_b32 s39, s27, s37
	s_cselect_b32 s38, s56, s36
	s_cselect_b32 s37, s25, s59
	s_cselect_b32 s36, s57, s58
	v_lshl_add_u64 v[182:183], s[34:35], 0, v[136:137]
	s_add_i32 m0, s41, 0xc000
	ds_read_b128 v[190:193], v157
	ds_read_b128 v[194:197], v157 offset:1024
	ds_read_b128 v[198:201], v157 offset:2048
	ds_read_b128 v[202:205], v157 offset:3072
	ds_read_b128 v[206:209], v157 offset:4096
	ds_read_b128 v[210:213], v157 offset:5120
	ds_read_b128 v[214:217], v157 offset:6144
	ds_read_b128 v[218:221], v157 offset:7168
	global_load_lds_dwordx4 v[182:183], off
	v_lshl_add_u64 v[182:183], s[34:35], 0, v[138:139]
	s_add_i32 m0, s41, 0xe000
	s_nop 0
	global_load_lds_dwordx4 v[182:183], off
	s_waitcnt vmcnt(8)
	s_waitcnt lgkmcnt(0)
	s_barrier
	s_setprio 1
	s_waitcnt lgkmcnt(0)
	v_mfma_f32_16x16x32_bf16 v[124:127], v[144:147], v[190:193], v[124:127]
	v_mfma_f32_16x16x32_bf16 v[120:123], v[158:161], v[190:193], v[120:123]
	v_mfma_f32_16x16x32_bf16 v[108:111], v[144:147], v[198:201], v[108:111]
	v_mfma_f32_16x16x32_bf16 v[104:107], v[158:161], v[198:201], v[104:107]
	v_mfma_f32_16x16x32_bf16 v[92:95], v[144:147], v[206:209], v[92:95]
	v_mfma_f32_16x16x32_bf16 v[88:91], v[158:161], v[206:209], v[88:91]
	v_mfma_f32_16x16x32_bf16 v[76:79], v[144:147], v[214:217], v[76:79]
	v_mfma_f32_16x16x32_bf16 v[72:75], v[158:161], v[214:217], v[72:75]
	v_mfma_f32_16x16x32_bf16 v[124:127], v[148:151], v[194:197], v[124:127]
	v_mfma_f32_16x16x32_bf16 v[120:123], v[162:165], v[194:197], v[120:123]
	v_mfma_f32_16x16x32_bf16 v[108:111], v[148:151], v[202:205], v[108:111]
	v_mfma_f32_16x16x32_bf16 v[104:107], v[162:165], v[202:205], v[104:107]
	v_mfma_f32_16x16x32_bf16 v[92:95], v[148:151], v[210:213], v[92:95]
	v_mfma_f32_16x16x32_bf16 v[88:91], v[162:165], v[210:213], v[88:91]
	v_mfma_f32_16x16x32_bf16 v[76:79], v[148:151], v[218:221], v[76:79]
	v_mfma_f32_16x16x32_bf16 v[72:75], v[162:165], v[218:221], v[72:75]
	s_setprio 0
	s_setprio 1
	v_mfma_f32_16x16x32_bf16 v[116:119], v[166:169], v[190:193], v[116:119]
	v_mfma_f32_16x16x32_bf16 v[112:115], v[174:177], v[190:193], v[112:115]
	v_mfma_f32_16x16x32_bf16 v[100:103], v[166:169], v[198:201], v[100:103]
	v_mfma_f32_16x16x32_bf16 v[96:99], v[174:177], v[198:201], v[96:99]
	v_mfma_f32_16x16x32_bf16 v[84:87], v[166:169], v[206:209], v[84:87]
	v_mfma_f32_16x16x32_bf16 v[80:83], v[174:177], v[206:209], v[80:83]
	v_mfma_f32_16x16x32_bf16 v[68:71], v[166:169], v[214:217], v[68:71]
	v_mfma_f32_16x16x32_bf16 v[64:67], v[174:177], v[214:217], v[64:67]
	v_mfma_f32_16x16x32_bf16 v[116:119], v[170:173], v[194:197], v[116:119]
	v_mfma_f32_16x16x32_bf16 v[112:115], v[178:181], v[194:197], v[112:115]
	v_mfma_f32_16x16x32_bf16 v[100:103], v[170:173], v[202:205], v[100:103]
	v_mfma_f32_16x16x32_bf16 v[96:99], v[178:181], v[202:205], v[96:99]
	v_mfma_f32_16x16x32_bf16 v[84:87], v[170:173], v[210:213], v[84:87]
	v_mfma_f32_16x16x32_bf16 v[80:83], v[178:181], v[210:213], v[80:83]
	v_mfma_f32_16x16x32_bf16 v[68:71], v[170:173], v[218:221], v[68:71]
	v_mfma_f32_16x16x32_bf16 v[64:67], v[178:181], v[218:221], v[64:67]
	s_setprio 0
	s_barrier
	s_add_i32 s61, s50, s3
	v_lshl_add_u64 v[182:183], s[36:37], 0, v[132:133]
	s_mov_b32 m0, s61
	ds_read_b128 v[190:193], v157 offset:16384
	ds_read_b128 v[194:197], v157 offset:17408
	ds_read_b128 v[198:201], v157 offset:18432
	ds_read_b128 v[202:205], v157 offset:19456
	ds_read_b128 v[206:209], v157 offset:20480
	ds_read_b128 v[210:213], v157 offset:21504
	ds_read_b128 v[214:217], v157 offset:22528
	ds_read_b128 v[218:221], v157 offset:23552
	global_load_lds_dwordx4 v[182:183], off
	s_add_i32 m0, s61, 0x2000
	s_add_u32 s62, s36, 0x80000
	v_lshl_add_u64 v[224:225], s[36:37], 0, v[128:129]
	s_addc_u32 s63, s37, 0
	s_add_i32 s61, s51, s3
	global_load_lds_dwordx4 v[224:225], off
	v_lshl_add_u64 v[226:227], s[62:63], 0, v[132:133]
	s_mov_b32 m0, s61
	v_lshl_add_u64 v[228:229], s[38:39], 0, v[130:131]
	global_load_lds_dwordx4 v[226:227], off
	v_lshl_add_u64 v[226:227], s[62:63], 0, v[128:129]
	s_add_i32 m0, s61, 0x2000
	s_nop 0
	global_load_lds_dwordx4 v[226:227], off
	v_lshl_add_u64 v[226:227], s[38:39], 0, v[134:135]
	s_mov_b32 m0, s41
	s_nop 0
	global_load_lds_dwordx4 v[226:227], off
	s_mov_b32 m0, s42
	s_nop 0
	global_load_lds_dwordx4 v[228:229], off
	s_waitcnt vmcnt(8)
	s_waitcnt lgkmcnt(0)
	s_barrier
; #define PG8_STAGE(bufoff, gbase, voff) do { _Pragma("unroll") for (int _i = 0; _i < 2; ++_i) \
;         __builtin_amdgcn_global_load_lds((const unsigned*)((const char*)(gbase) + (voff)[_i]), (LAS unsigned*)(lds + (bufoff) + ldsw + _i * 8192), 16, 0, 0); } while (0)
; #define PG8_LDA(dst, b, h) do { _Pragma("unroll") for (int m = 0; m < 4; ++m) _Pragma("unroll") for (int k = 0; k < 2; ++k) dst[m][k] = *(const LAS bf16x8*)(lds + PG8_SA(b, h) + aoff + m * 2048 + k * 1024); } while (0)
; #define PG8_LDB(dst, b, h) do { _Pragma("unroll") for (int n = 0; n < 2; ++n) _Pragma("unroll") for (int k = 0; k < 2; ++k) dst[n][k] = *(const LAS bf16x8*)(lds + PG8_SB(b, h) + boff + n * 2048 + k * 1024); } while (0)
; #define PG8_MMA(ai, bj, At, Bt) do { __builtin_amdgcn_s_setprio(1); _Pragma("unroll") for (int m = 0; m < 4; ++m) _Pragma("unroll") for (int n = 0; n < 2; ++n) _Pragma("unroll") for (int k = 0; k < 2; ++k) \
;         acc[ai][bj][m][n] = __builtin_amdgcn_mfma_f32_16x16x32_bf16(Bt[n][k], At[m][k], acc[ai][bj][m][n], 0, 0, 0); __builtin_amdgcn_s_setprio(0); } while (0)
; #define PG8_WAIT_V(n) asm volatile("s_waitcnt vmcnt(" #n ")" ::: "memory")
; #define PG8_WAIT_L(n) asm volatile("s_waitcnt lgkmcnt(" #n ")" ::: "memory")
; #define PG8_BAR __builtin_amdgcn_s_barrier()
; #define PG8_SCHED __builtin_amdgcn_sched_barrier(0)
; template <class Epi, class Sched>
; __device__ __forceinline__ void gemm_phase(LAS unsigned char* lds, const Gemm g, const Sched& S, const Epi& E) {
;     ...
;             PG8_WAIT_V(8); PG8_WAIT_L(0); PG8_BAR; PG8_MMA(1, 0, At, B0); PG8_MMA(1, 1, At, B1); PG8_BAR; PG8_SCHED;
;             PG8_LDB(B0, 1, 0); PG8_LDB(B1, 1, 1); PG8_SCHED; PG8_LDA(At, 1, 0); PG8_STAGE(PG8_SA(0, 1), a2 + hstepA, voffA);
;             PG8_WAIT_V(8); PG8_WAIT_L(0); PG8_BAR; PG8_MMA(0, 0, At, B0); PG8_MMA(0, 1, At, B1); PG8_BAR; PG8_SCHED;
	s_setprio 1
	s_waitcnt lgkmcnt(0)
	v_mfma_f32_16x16x32_bf16 v[60:63], v[144:147], v[190:193], v[60:63]
	v_mfma_f32_16x16x32_bf16 v[56:59], v[158:161], v[190:193], v[56:59]
	v_mfma_f32_16x16x32_bf16 v[44:47], v[144:147], v[198:201], v[44:47]
	v_mfma_f32_16x16x32_bf16 v[40:43], v[158:161], v[198:201], v[40:43]
	v_mfma_f32_16x16x32_bf16 v[28:31], v[144:147], v[206:209], v[28:31]
	v_mfma_f32_16x16x32_bf16 v[24:27], v[158:161], v[206:209], v[24:27]
	v_mfma_f32_16x16x32_bf16 v[12:15], v[144:147], v[214:217], v[12:15]
	v_mfma_f32_16x16x32_bf16 v[8:11], v[158:161], v[214:217], v[8:11]
	v_mfma_f32_16x16x32_bf16 v[60:63], v[148:151], v[194:197], v[60:63]
	v_mfma_f32_16x16x32_bf16 v[56:59], v[162:165], v[194:197], v[56:59]
	v_mfma_f32_16x16x32_bf16 v[44:47], v[148:151], v[202:205], v[44:47]
	v_mfma_f32_16x16x32_bf16 v[40:43], v[162:165], v[202:205], v[40:43]
	v_mfma_f32_16x16x32_bf16 v[28:31], v[148:151], v[210:213], v[28:31]
	v_mfma_f32_16x16x32_bf16 v[24:27], v[162:165], v[210:213], v[24:27]
	v_mfma_f32_16x16x32_bf16 v[12:15], v[148:151], v[218:221], v[12:15]
	v_mfma_f32_16x16x32_bf16 v[8:11], v[162:165], v[218:221], v[8:11]
	s_setprio 0
	s_setprio 1
	v_mfma_f32_16x16x32_bf16 v[52:55], v[166:169], v[190:193], v[52:55]
	v_mfma_f32_16x16x32_bf16 v[48:51], v[174:177], v[190:193], v[48:51]
	v_mfma_f32_16x16x32_bf16 v[36:39], v[166:169], v[198:201], v[36:39]
	v_mfma_f32_16x16x32_bf16 v[32:35], v[174:177], v[198:201], v[32:35]
	v_mfma_f32_16x16x32_bf16 v[20:23], v[166:169], v[206:209], v[20:23]
	v_mfma_f32_16x16x32_bf16 v[16:19], v[174:177], v[206:209], v[16:19]
	v_mfma_f32_16x16x32_bf16 v[4:7], v[166:169], v[214:217], v[4:7]
	v_mfma_f32_16x16x32_bf16 v[0:3], v[174:177], v[214:217], v[0:3]
	v_mfma_f32_16x16x32_bf16 v[52:55], v[170:173], v[194:197], v[52:55]
	v_mfma_f32_16x16x32_bf16 v[48:51], v[178:181], v[194:197], v[48:51]
	v_mfma_f32_16x16x32_bf16 v[36:39], v[170:173], v[202:205], v[36:39]
	v_mfma_f32_16x16x32_bf16 v[32:35], v[178:181], v[202:205], v[32:35]
	v_mfma_f32_16x16x32_bf16 v[20:23], v[170:173], v[210:213], v[20:23]
	v_mfma_f32_16x16x32_bf16 v[16:19], v[178:181], v[210:213], v[16:19]
	v_mfma_f32_16x16x32_bf16 v[4:7], v[170:173], v[218:221], v[4:7]
	v_mfma_f32_16x16x32_bf16 v[0:3], v[178:181], v[218:221], v[0:3]
	s_setprio 0
	s_barrier
	s_add_i32 s61, 0, 0x18000
	s_add_i32 s62, 0, 0x1c000
	v_add_u32_e32 v162, s61, v153
	v_add_u32_e32 v178, s62, v153
	ds_read_b128 v[144:147], v162
	ds_read_b128 v[148:151], v162 offset:1024
	ds_read_b128 v[158:161], v162 offset:2048
	ds_read_b128 v[162:165], v162 offset:3072
	ds_read_b128 v[166:169], v178
	ds_read_b128 v[170:173], v178 offset:1024
	ds_read_b128 v[174:177], v178 offset:2048
	ds_read_b128 v[178:181], v178 offset:3072
	s_add_u32 s38, s38, 0x80000
	s_addc_u32 s39, s39, 0
	s_mov_b32 m0, s43
	v_lshl_add_u64 v[230:231], s[38:39], 0, v[134:135]
	ds_read_b128 v[190:193], v157 offset:32768
	ds_read_b128 v[194:197], v157 offset:33792
	ds_read_b128 v[198:201], v157 offset:34816
	ds_read_b128 v[202:205], v157 offset:35840
	ds_read_b128 v[206:209], v157 offset:36864
	ds_read_b128 v[210:213], v157 offset:37888
	ds_read_b128 v[214:217], v157 offset:38912
	ds_read_b128 v[218:221], v157 offset:39936
	global_load_lds_dwordx4 v[230:231], off
	v_lshl_add_u64 v[230:231], s[38:39], 0, v[130:131]
	s_mov_b32 m0, s44
	s_nop 0
	global_load_lds_dwordx4 v[230:231], off
	s_waitcnt vmcnt(8)
	s_waitcnt lgkmcnt(0)
	s_barrier
	s_setprio 1
	s_waitcnt lgkmcnt(0)
	v_mfma_f32_16x16x32_bf16 v[124:127], v[144:147], v[190:193], v[124:127]
	v_mfma_f32_16x16x32_bf16 v[120:123], v[158:161], v[190:193], v[120:123]
	v_mfma_f32_16x16x32_bf16 v[108:111], v[144:147], v[198:201], v[108:111]
	v_mfma_f32_16x16x32_bf16 v[104:107], v[158:161], v[198:201], v[104:107]
	v_mfma_f32_16x16x32_bf16 v[92:95], v[144:147], v[206:209], v[92:95]
	v_mfma_f32_16x16x32_bf16 v[88:91], v[158:161], v[206:209], v[88:91]
	v_mfma_f32_16x16x32_bf16 v[76:79], v[144:147], v[214:217], v[76:79]
	v_mfma_f32_16x16x32_bf16 v[72:75], v[158:161], v[214:217], v[72:75]
	v_mfma_f32_16x16x32_bf16 v[124:127], v[148:151], v[194:197], v[124:127]
	v_mfma_f32_16x16x32_bf16 v[120:123], v[162:165], v[194:197], v[120:123]
	v_mfma_f32_16x16x32_bf16 v[108:111], v[148:151], v[202:205], v[108:111]
	v_mfma_f32_16x16x32_bf16 v[104:107], v[162:165], v[202:205], v[104:107]
	v_mfma_f32_16x16x32_bf16 v[92:95], v[148:151], v[210:213], v[92:95]
	v_mfma_f32_16x16x32_bf16 v[88:91], v[162:165], v[210:213], v[88:91]
	v_mfma_f32_16x16x32_bf16 v[76:79], v[148:151], v[218:221], v[76:79]
	v_mfma_f32_16x16x32_bf16 v[72:75], v[162:165], v[218:221], v[72:75]
	s_setprio 0
	s_setprio 1
	v_mfma_f32_16x16x32_bf16 v[116:119], v[166:169], v[190:193], v[116:119]
	v_mfma_f32_16x16x32_bf16 v[112:115], v[174:177], v[190:193], v[112:115]
	v_mfma_f32_16x16x32_bf16 v[100:103], v[166:169], v[198:201], v[100:103]
	v_mfma_f32_16x16x32_bf16 v[96:99], v[174:177], v[198:201], v[96:99]
	v_mfma_f32_16x16x32_bf16 v[84:87], v[166:169], v[206:209], v[84:87]
	v_mfma_f32_16x16x32_bf16 v[80:83], v[174:177], v[206:209], v[80:83]
	v_mfma_f32_16x16x32_bf16 v[68:71], v[166:169], v[214:217], v[68:71]
	v_mfma_f32_16x16x32_bf16 v[64:67], v[174:177], v[214:217], v[64:67]
	v_mfma_f32_16x16x32_bf16 v[116:119], v[170:173], v[194:197], v[116:119]
	v_mfma_f32_16x16x32_bf16 v[112:115], v[178:181], v[194:197], v[112:115]
	v_mfma_f32_16x16x32_bf16 v[100:103], v[170:173], v[202:205], v[100:103]
	v_mfma_f32_16x16x32_bf16 v[96:99], v[178:181], v[202:205], v[96:99]
	v_mfma_f32_16x16x32_bf16 v[84:87], v[170:173], v[210:213], v[84:87]
	v_mfma_f32_16x16x32_bf16 v[80:83], v[178:181], v[210:213], v[80:83]
	v_mfma_f32_16x16x32_bf16 v[68:71], v[170:173], v[218:221], v[68:71]
	v_mfma_f32_16x16x32_bf16 v[64:67], v[178:181], v[218:221], v[64:67]
	s_setprio 0
	s_barrier
; #define PG8_STAGE(bufoff, gbase, voff) do { _Pragma("unroll") for (int _i = 0; _i < 2; ++_i) \
;         __builtin_amdgcn_global_load_lds((const unsigned*)((const char*)(gbase) + (voff)[_i]), (LAS unsigned*)(lds + (bufoff) + ldsw + _i * 8192), 16, 0, 0); } while (0)
; #define PG8_LDA(dst, b, h) do { _Pragma("unroll") for (int m = 0; m < 4; ++m) _Pragma("unroll") for (int k = 0; k < 2; ++k) dst[m][k] = *(const LAS bf16x8*)(lds + PG8_SA(b, h) + aoff + m * 2048 + k * 1024); } while (0)
; #define PG8_MMA(ai, bj, At, Bt) do { __builtin_amdgcn_s_setprio(1); _Pragma("unroll") for (int m = 0; m < 4; ++m) _Pragma("unroll") for (int n = 0; n < 2; ++n) _Pragma("unroll") for (int k = 0; k < 2; ++k) \
;         acc[ai][bj][m][n] = __builtin_amdgcn_mfma_f32_16x16x32_bf16(Bt[n][k], At[m][k], acc[ai][bj][m][n], 0, 0, 0); __builtin_amdgcn_s_setprio(0); } while (0)
; #define PG8_WAIT_V(n) asm volatile("s_waitcnt vmcnt(" #n ")" ::: "memory")
; #define PG8_WAIT_L(n) asm volatile("s_waitcnt lgkmcnt(" #n ")" ::: "memory")
; #define PG8_BAR __builtin_amdgcn_s_barrier()
; #define PG8_SCHED __builtin_amdgcn_sched_barrier(0)
; template <class Epi, class Sched>
; __device__ __forceinline__ void gemm_phase(LAS unsigned char* lds, const Gemm g, const Sched& S, const Epi& E) {
;     ...
;         for (int t = 0; t < nt; t += 2) {
;             const bool last = (t == nt - 2);
;     ...
;             PG8_LDA(At, 1, 1); PG8_STAGE(PG8_SB(1, 0), b3, voffB); PG8_STAGE(PG8_SB(1, 1), b3 + hstepB, voffB); PG8_STAGE(PG8_SA(1, 0), a3, voffA);
;             PG8_WAIT_V(8); PG8_WAIT_L(0); PG8_BAR; PG8_MMA(1, 0, At, B0); PG8_MMA(1, 1, At, B1); PG8_BAR; PG8_SCHED;
	s_add_i32 s38, s61, s3
	v_lshl_add_u64 v[182:183], v[182:183], 0, s[10:11]
	s_mov_b32 m0, s38
	ds_read_b128 v[190:193], v157 offset:49152
	ds_read_b128 v[194:197], v157 offset:50176
	ds_read_b128 v[198:201], v157 offset:51200
	ds_read_b128 v[202:205], v157 offset:52224
	ds_read_b128 v[206:209], v157 offset:53248
	ds_read_b128 v[210:213], v157 offset:54272
	ds_read_b128 v[214:217], v157 offset:55296
	ds_read_b128 v[218:221], v157 offset:56320
	global_load_lds_dwordx4 v[182:183], off
	s_add_i32 m0, s38, 0x2000
	s_add_u32 s36, s36, 0x80080
	v_lshl_add_u64 v[182:183], v[224:225], 0, s[10:11]
	s_addc_u32 s37, s37, 0
	s_add_i32 s38, s62, s3
	global_load_lds_dwordx4 v[182:183], off
	v_lshl_add_u64 v[182:183], s[36:37], 0, v[132:133]
	s_mov_b32 m0, s38
	s_nop 0
	global_load_lds_dwordx4 v[182:183], off
	v_lshl_add_u64 v[182:183], s[36:37], 0, v[128:129]
	s_add_i32 m0, s38, 0x2000
	s_nop 0
	global_load_lds_dwordx4 v[182:183], off
	v_lshl_add_u64 v[182:183], v[226:227], 0, s[10:11]
	s_mov_b32 m0, s46
	s_nop 0
	global_load_lds_dwordx4 v[182:183], off
	v_lshl_add_u64 v[182:183], v[228:229], 0, s[10:11]
	s_mov_b32 m0, s47
	s_nop 0
	global_load_lds_dwordx4 v[182:183], off
	s_waitcnt vmcnt(8)
	s_waitcnt lgkmcnt(0)
	s_barrier
	s_setprio 1
	s_waitcnt lgkmcnt(0)
	v_mfma_f32_16x16x32_bf16 v[60:63], v[144:147], v[190:193], v[60:63]
	v_mfma_f32_16x16x32_bf16 v[56:59], v[158:161], v[190:193], v[56:59]
	s_add_i32 s60, s60, 2
	v_mfma_f32_16x16x32_bf16 v[44:47], v[144:147], v[198:201], v[44:47]
	s_add_u32 s34, s34, 0x100
	v_mfma_f32_16x16x32_bf16 v[40:43], v[158:161], v[198:201], v[40:43]
	s_addc_u32 s35, s35, 0
	v_mfma_f32_16x16x32_bf16 v[28:31], v[144:147], v[206:209], v[28:31]
	s_add_u32 s58, s58, 0x100
	v_mfma_f32_16x16x32_bf16 v[24:27], v[158:161], v[206:209], v[24:27]
	s_addc_u32 s59, s59, 0
	v_mfma_f32_16x16x32_bf16 v[12:15], v[144:147], v[214:217], v[12:15]
	s_cmp_gt_u32 s60, 29
	v_mfma_f32_16x16x32_bf16 v[8:11], v[158:161], v[214:217], v[8:11]
	v_mfma_f32_16x16x32_bf16 v[60:63], v[148:151], v[194:197], v[60:63]
	v_mfma_f32_16x16x32_bf16 v[56:59], v[162:165], v[194:197], v[56:59]
	v_mfma_f32_16x16x32_bf16 v[44:47], v[148:151], v[202:205], v[44:47]
	v_mfma_f32_16x16x32_bf16 v[40:43], v[162:165], v[202:205], v[40:43]
	v_mfma_f32_16x16x32_bf16 v[28:31], v[148:151], v[210:213], v[28:31]
	v_mfma_f32_16x16x32_bf16 v[24:27], v[162:165], v[210:213], v[24:27]
	v_mfma_f32_16x16x32_bf16 v[12:15], v[148:151], v[218:221], v[12:15]
	v_mfma_f32_16x16x32_bf16 v[8:11], v[162:165], v[218:221], v[8:11]
	s_setprio 0
	s_setprio 1
	v_mfma_f32_16x16x32_bf16 v[52:55], v[166:169], v[190:193], v[52:55]
	v_mfma_f32_16x16x32_bf16 v[48:51], v[174:177], v[190:193], v[48:51]
	v_mfma_f32_16x16x32_bf16 v[36:39], v[166:169], v[198:201], v[36:39]
	v_mfma_f32_16x16x32_bf16 v[32:35], v[174:177], v[198:201], v[32:35]
	v_mfma_f32_16x16x32_bf16 v[20:23], v[166:169], v[206:209], v[20:23]
	v_mfma_f32_16x16x32_bf16 v[16:19], v[174:177], v[206:209], v[16:19]
	v_mfma_f32_16x16x32_bf16 v[4:7], v[166:169], v[214:217], v[4:7]
	v_mfma_f32_16x16x32_bf16 v[0:3], v[174:177], v[214:217], v[0:3]
	v_mfma_f32_16x16x32_bf16 v[52:55], v[170:173], v[194:197], v[52:55]
	v_mfma_f32_16x16x32_bf16 v[48:51], v[178:181], v[194:197], v[48:51]
	v_mfma_f32_16x16x32_bf16 v[36:39], v[170:173], v[202:205], v[36:39]
	v_mfma_f32_16x16x32_bf16 v[32:35], v[178:181], v[202:205], v[32:35]
	v_mfma_f32_16x16x32_bf16 v[20:23], v[170:173], v[210:213], v[20:23]
	v_mfma_f32_16x16x32_bf16 v[16:19], v[178:181], v[210:213], v[16:19]
	v_mfma_f32_16x16x32_bf16 v[4:7], v[170:173], v[218:221], v[4:7]
	v_mfma_f32_16x16x32_bf16 v[0:3], v[178:181], v[218:221], v[0:3]
	s_setprio 0
	s_barrier
	s_cbranch_scc0 .LBB0_933
	s_and_b64 vcc, exec, s[14:15]
	s_cbranch_vccz .LBB0_936
	s_barrier

; #define PG8_STAGE(bufoff, gbase, voff) do { _Pragma("unroll") for (int _i = 0; _i < 2; ++_i) \
;         __builtin_amdgcn_global_load_lds((const unsigned*)((const char*)(gbase) + (voff)[_i]), (LAS unsigned*)(lds + (bufoff) + ldsw + _i * 8192), 16, 0, 0); } while (0)
; #define PG8_LDA(dst, b, h) do { _Pragma("unroll") for (int m = 0; m < 4; ++m) _Pragma("unroll") for (int k = 0; k < 2; ++k) dst[m][k] = *(const LAS bf16x8*)(lds + PG8_SA(b, h) + aoff + m * 2048 + k * 1024); } while (0)
; #define PG8_LDB(dst, b, h) do { _Pragma("unroll") for (int n = 0; n < 2; ++n) _Pragma("unroll") for (int k = 0; k < 2; ++k) dst[n][k] = *(const LAS bf16x8*)(lds + PG8_SB(b, h) + boff + n * 2048 + k * 1024); } while (0)
; #define PG8_MMA(ai, bj, At, Bt) do { __builtin_amdgcn_s_setprio(1); _Pragma("unroll") for (int m = 0; m < 4; ++m) _Pragma("unroll") for (int n = 0; n < 2; ++n) _Pragma("unroll") for (int k = 0; k < 2; ++k) \
;         acc[ai][bj][m][n] = __builtin_amdgcn_mfma_f32_16x16x32_bf16(Bt[n][k], At[m][k], acc[ai][bj][m][n], 0, 0, 0); __builtin_amdgcn_s_setprio(0); } while (0)
; #define PG8_WAIT_V(n) asm volatile("s_waitcnt vmcnt(" #n ")" ::: "memory")
; #define PG8_WAIT_L(n) asm volatile("s_waitcnt lgkmcnt(" #n ")" ::: "memory")
; #define PG8_BAR __builtin_amdgcn_s_barrier()
; #define PG8_SCHED __builtin_amdgcn_sched_barrier(0)
; template <class Epi, class Sched>
; __device__ __forceinline__ void gemm_phase(LAS unsigned char* lds, const Gemm g, const Sched& S, const Epi& E) {
;     ...
;         for (int t = 0; t < nt; t += 2) {
;             const bool last = (t == nt - 2);
;             const char* a1 = cA + (size_t)(t + 1) * kstep;
;             const char* a2 = last ? nA : cA + (size_t)(t + 2) * kstep; const char* b2 = last ? nB : cB + (size_t)(t + 2) * kstep;
;             const char* a3 = a2 + kstep; const char* b3 = b2 + kstep;
;             PG8_LDB(B0, 0, 0); PG8_LDB(B1, 0, 1); PG8_SCHED; PG8_LDA(At, 0, 0); PG8_STAGE(PG8_SA(1, 1), a1 + hstepA, voffA);
;             PG8_WAIT_V(8); PG8_WAIT_L(0); PG8_BAR; PG8_MMA(0, 0, At, B0); PG8_MMA(0, 1, At, B1); PG8_BAR; PG8_SCHED;
;             PG8_LDA(At, 0, 1); PG8_STAGE(PG8_SB(0, 0), b2, voffB); PG8_STAGE(PG8_SB(0, 1), b2 + hstepB, voffB); PG8_STAGE(PG8_SA(0, 0), a2, voffA);
.LBB0_1028:
	ds_read_b128 v[128:131], v191
	ds_read_b128 v[132:135], v191 offset:1024
	ds_read_b128 v[136:139], v191 offset:2048
	ds_read_b128 v[140:143], v191 offset:3072
	ds_read_b128 v[144:147], v192
	ds_read_b128 v[148:151], v192 offset:1024
	ds_read_b128 v[168:171], v192 offset:2048
	ds_read_b128 v[172:175], v192 offset:3072
	s_add_u32 s34, s30, 0x100
	s_addc_u32 s35, s31, 0
	s_cmpk_eq_i32 s55, 0x7c
	s_cselect_b32 s39, s23, s35
	s_cselect_b32 s38, s29, s34
	s_cselect_b32 s37, s21, s54
	s_cselect_b32 s36, s52, s53
	v_lshl_add_u64 v[188:189], s[30:31], 0, v[160:161]
	s_add_i32 m0, s33, 0xc000
	ds_read_b128 v[176:179], v193
	ds_read_b128 v[180:183], v193 offset:1024
	ds_read_b128 v[196:199], v193 offset:2048
	ds_read_b128 v[200:203], v193 offset:3072
	ds_read_b128 v[204:207], v193 offset:4096
	ds_read_b128 v[208:211], v193 offset:5120
	ds_read_b128 v[212:215], v193 offset:6144
	ds_read_b128 v[216:219], v193 offset:7168
	global_load_lds_dwordx4 v[188:189], off
	v_lshl_add_u64 v[188:189], s[30:31], 0, v[162:163]
	s_add_i32 m0, s33, 0xe000
	s_nop 0
	global_load_lds_dwordx4 v[188:189], off
	s_waitcnt vmcnt(8)
	s_waitcnt lgkmcnt(0)
	s_barrier
	s_setprio 1
	s_waitcnt lgkmcnt(0)
	v_mfma_f32_16x16x32_bf16 v[124:127], v[128:131], v[176:179], v[124:127]
	v_mfma_f32_16x16x32_bf16 v[120:123], v[136:139], v[176:179], v[120:123]
	v_mfma_f32_16x16x32_bf16 v[108:111], v[128:131], v[196:199], v[108:111]
	v_mfma_f32_16x16x32_bf16 v[104:107], v[136:139], v[196:199], v[104:107]
	v_mfma_f32_16x16x32_bf16 v[92:95], v[128:131], v[204:207], v[92:95]
	v_mfma_f32_16x16x32_bf16 v[88:91], v[136:139], v[204:207], v[88:91]
	v_mfma_f32_16x16x32_bf16 v[76:79], v[128:131], v[212:215], v[76:79]
	v_mfma_f32_16x16x32_bf16 v[72:75], v[136:139], v[212:215], v[72:75]
	v_mfma_f32_16x16x32_bf16 v[124:127], v[132:135], v[180:183], v[124:127]
	v_mfma_f32_16x16x32_bf16 v[120:123], v[140:143], v[180:183], v[120:123]
	v_mfma_f32_16x16x32_bf16 v[108:111], v[132:135], v[200:203], v[108:111]
	v_mfma_f32_16x16x32_bf16 v[104:107], v[140:143], v[200:203], v[104:107]
	v_mfma_f32_16x16x32_bf16 v[92:95], v[132:135], v[208:211], v[92:95]
	v_mfma_f32_16x16x32_bf16 v[88:91], v[140:143], v[208:211], v[88:91]
	v_mfma_f32_16x16x32_bf16 v[76:79], v[132:135], v[216:219], v[76:79]
	v_mfma_f32_16x16x32_bf16 v[72:75], v[140:143], v[216:219], v[72:75]
	s_setprio 0
	s_setprio 1
	v_mfma_f32_16x16x32_bf16 v[116:119], v[144:147], v[176:179], v[116:119]
	v_mfma_f32_16x16x32_bf16 v[112:115], v[168:171], v[176:179], v[112:115]
	v_mfma_f32_16x16x32_bf16 v[100:103], v[144:147], v[196:199], v[100:103]
	v_mfma_f32_16x16x32_bf16 v[96:99], v[168:171], v[196:199], v[96:99]
	v_mfma_f32_16x16x32_bf16 v[84:87], v[144:147], v[204:207], v[84:87]
	v_mfma_f32_16x16x32_bf16 v[80:83], v[168:171], v[204:207], v[80:83]
	v_mfma_f32_16x16x32_bf16 v[68:71], v[144:147], v[212:215], v[68:71]
	v_mfma_f32_16x16x32_bf16 v[64:67], v[168:171], v[212:215], v[64:67]
	v_mfma_f32_16x16x32_bf16 v[116:119], v[148:151], v[180:183], v[116:119]
	v_mfma_f32_16x16x32_bf16 v[112:115], v[172:175], v[180:183], v[112:115]
	v_mfma_f32_16x16x32_bf16 v[100:103], v[148:151], v[200:203], v[100:103]
	v_mfma_f32_16x16x32_bf16 v[96:99], v[172:175], v[200:203], v[96:99]
	v_mfma_f32_16x16x32_bf16 v[84:87], v[148:151], v[208:211], v[84:87]
	v_mfma_f32_16x16x32_bf16 v[80:83], v[172:175], v[208:211], v[80:83]
	v_mfma_f32_16x16x32_bf16 v[68:71], v[148:151], v[216:219], v[68:71]
	v_mfma_f32_16x16x32_bf16 v[64:67], v[172:175], v[216:219], v[64:67]
	s_setprio 0
	s_barrier
	s_add_i32 s30, s49, s3
	v_lshl_add_u64 v[188:189], s[36:37], 0, v[154:155]
	s_mov_b32 m0, s30
	ds_read_b128 v[176:179], v193 offset:16384
	ds_read_b128 v[180:183], v193 offset:17408
	ds_read_b128 v[196:199], v193 offset:18432
	ds_read_b128 v[200:203], v193 offset:19456
	ds_read_b128 v[204:207], v193 offset:20480
	ds_read_b128 v[208:211], v193 offset:21504
	ds_read_b128 v[212:215], v193 offset:22528
	ds_read_b128 v[216:219], v193 offset:23552
	global_load_lds_dwordx4 v[188:189], off
	s_add_i32 m0, s30, 0x2000
	s_add_u32 s30, s36, 0x200000
	v_lshl_add_u64 v[220:221], s[36:37], 0, v[158:159]
	s_addc_u32 s31, s37, 0
	s_add_i32 s56, s50, s3
	global_load_lds_dwordx4 v[220:221], off
	v_lshl_add_u64 v[222:223], s[30:31], 0, v[154:155]
	s_mov_b32 m0, s56
	v_lshl_add_u64 v[224:225], s[38:39], 0, v[156:157]
	global_load_lds_dwordx4 v[222:223], off
	v_lshl_add_u64 v[222:223], s[30:31], 0, v[158:159]
	s_add_i32 m0, s56, 0x2000
	s_nop 0
	global_load_lds_dwordx4 v[222:223], off
	v_lshl_add_u64 v[222:223], s[38:39], 0, v[152:153]
	s_mov_b32 m0, s33
	s_nop 0
	global_load_lds_dwordx4 v[222:223], off
	s_mov_b32 m0, s40
	s_nop 0
	global_load_lds_dwordx4 v[224:225], off
	s_waitcnt vmcnt(8)
	s_waitcnt lgkmcnt(0)
	s_barrier
; #define PG8_STAGE(bufoff, gbase, voff) do { _Pragma("unroll") for (int _i = 0; _i < 2; ++_i) \
;         __builtin_amdgcn_global_load_lds((const unsigned*)((const char*)(gbase) + (voff)[_i]), (LAS unsigned*)(lds + (bufoff) + ldsw + _i * 8192), 16, 0, 0); } while (0)
; #define PG8_LDA(dst, b, h) do { _Pragma("unroll") for (int m = 0; m < 4; ++m) _Pragma("unroll") for (int k = 0; k < 2; ++k) dst[m][k] = *(const LAS bf16x8*)(lds + PG8_SA(b, h) + aoff + m * 2048 + k * 1024); } while (0)
; #define PG8_LDB(dst, b, h) do { _Pragma("unroll") for (int n = 0; n < 2; ++n) _Pragma("unroll") for (int k = 0; k < 2; ++k) dst[n][k] = *(const LAS bf16x8*)(lds + PG8_SB(b, h) + boff + n * 2048 + k * 1024); } while (0)
; #define PG8_MMA(ai, bj, At, Bt) do { __builtin_amdgcn_s_setprio(1); _Pragma("unroll") for (int m = 0; m < 4; ++m) _Pragma("unroll") for (int n = 0; n < 2; ++n) _Pragma("unroll") for (int k = 0; k < 2; ++k) \
;         acc[ai][bj][m][n] = __builtin_amdgcn_mfma_f32_16x16x32_bf16(Bt[n][k], At[m][k], acc[ai][bj][m][n], 0, 0, 0); __builtin_amdgcn_s_setprio(0); } while (0)
; #define PG8_WAIT_V(n) asm volatile("s_waitcnt vmcnt(" #n ")" ::: "memory")
; #define PG8_WAIT_L(n) asm volatile("s_waitcnt lgkmcnt(" #n ")" ::: "memory")
; #define PG8_BAR __builtin_amdgcn_s_barrier()
; #define PG8_SCHED __builtin_amdgcn_sched_barrier(0)
; template <class Epi, class Sched>
; __device__ __forceinline__ void gemm_phase(LAS unsigned char* lds, const Gemm g, const Sched& S, const Epi& E) {
;     ...
;             PG8_WAIT_V(8); PG8_WAIT_L(0); PG8_BAR; PG8_MMA(1, 0, At, B0); PG8_MMA(1, 1, At, B1); PG8_BAR; PG8_SCHED;
;             PG8_LDB(B0, 1, 0); PG8_LDB(B1, 1, 1); PG8_SCHED; PG8_LDA(At, 1, 0); PG8_STAGE(PG8_SA(0, 1), a2 + hstepA, voffA);
;             PG8_WAIT_V(8); PG8_WAIT_L(0); PG8_BAR; PG8_MMA(0, 0, At, B0); PG8_MMA(0, 1, At, B1); PG8_BAR; PG8_SCHED;
	s_setprio 1
	s_waitcnt lgkmcnt(0)
	v_mfma_f32_16x16x32_bf16 v[60:63], v[128:131], v[176:179], v[60:63]
	v_mfma_f32_16x16x32_bf16 v[56:59], v[136:139], v[176:179], v[56:59]
	v_mfma_f32_16x16x32_bf16 v[44:47], v[128:131], v[196:199], v[44:47]
	v_mfma_f32_16x16x32_bf16 v[40:43], v[136:139], v[196:199], v[40:43]
	v_mfma_f32_16x16x32_bf16 v[28:31], v[128:131], v[204:207], v[28:31]
	v_mfma_f32_16x16x32_bf16 v[24:27], v[136:139], v[204:207], v[24:27]
	v_mfma_f32_16x16x32_bf16 v[12:15], v[128:131], v[212:215], v[12:15]
	v_mfma_f32_16x16x32_bf16 v[8:11], v[136:139], v[212:215], v[8:11]
	v_mfma_f32_16x16x32_bf16 v[60:63], v[132:135], v[180:183], v[60:63]
	v_mfma_f32_16x16x32_bf16 v[56:59], v[140:143], v[180:183], v[56:59]
	v_mfma_f32_16x16x32_bf16 v[44:47], v[132:135], v[200:203], v[44:47]
	v_mfma_f32_16x16x32_bf16 v[40:43], v[140:143], v[200:203], v[40:43]
	v_mfma_f32_16x16x32_bf16 v[28:31], v[132:135], v[208:211], v[28:31]
	v_mfma_f32_16x16x32_bf16 v[24:27], v[140:143], v[208:211], v[24:27]
	v_mfma_f32_16x16x32_bf16 v[12:15], v[132:135], v[216:219], v[12:15]
	v_mfma_f32_16x16x32_bf16 v[8:11], v[140:143], v[216:219], v[8:11]
	s_setprio 0
	s_setprio 1
	v_mfma_f32_16x16x32_bf16 v[52:55], v[144:147], v[176:179], v[52:55]
	v_mfma_f32_16x16x32_bf16 v[48:51], v[168:171], v[176:179], v[48:51]
	v_mfma_f32_16x16x32_bf16 v[36:39], v[144:147], v[196:199], v[36:39]
	v_mfma_f32_16x16x32_bf16 v[32:35], v[168:171], v[196:199], v[32:35]
	v_mfma_f32_16x16x32_bf16 v[20:23], v[144:147], v[204:207], v[20:23]
	v_mfma_f32_16x16x32_bf16 v[16:19], v[168:171], v[204:207], v[16:19]
	v_mfma_f32_16x16x32_bf16 v[4:7], v[144:147], v[212:215], v[4:7]
	v_mfma_f32_16x16x32_bf16 v[0:3], v[168:171], v[212:215], v[0:3]
	v_mfma_f32_16x16x32_bf16 v[52:55], v[148:151], v[180:183], v[52:55]
	v_mfma_f32_16x16x32_bf16 v[48:51], v[172:175], v[180:183], v[48:51]
	v_mfma_f32_16x16x32_bf16 v[36:39], v[148:151], v[200:203], v[36:39]
	v_mfma_f32_16x16x32_bf16 v[32:35], v[172:175], v[200:203], v[32:35]
	v_mfma_f32_16x16x32_bf16 v[20:23], v[148:151], v[208:211], v[20:23]
	v_mfma_f32_16x16x32_bf16 v[16:19], v[172:175], v[208:211], v[16:19]
	v_mfma_f32_16x16x32_bf16 v[4:7], v[148:151], v[216:219], v[4:7]
	v_mfma_f32_16x16x32_bf16 v[0:3], v[172:175], v[216:219], v[0:3]
	s_setprio 0
	s_barrier
	s_add_i32 s56, 0, 0x18000
	s_add_i32 s57, 0, 0x1c000
	v_add_u32_e32 v140, s56, v187
	v_add_u32_e32 v172, s57, v187
	ds_read_b128 v[128:131], v140
	ds_read_b128 v[132:135], v140 offset:1024
	ds_read_b128 v[136:139], v140 offset:2048
	ds_read_b128 v[140:143], v140 offset:3072
	ds_read_b128 v[144:147], v172
	ds_read_b128 v[148:151], v172 offset:1024
	ds_read_b128 v[168:171], v172 offset:2048
	ds_read_b128 v[172:175], v172 offset:3072
	s_add_u32 s30, s38, 0x200000
	s_addc_u32 s31, s39, 0
	s_mov_b32 m0, s41
	v_lshl_add_u64 v[226:227], s[30:31], 0, v[152:153]
	ds_read_b128 v[176:179], v193 offset:32768
	ds_read_b128 v[180:183], v193 offset:33792
	ds_read_b128 v[196:199], v193 offset:34816
	ds_read_b128 v[200:203], v193 offset:35840
	ds_read_b128 v[204:207], v193 offset:36864
	ds_read_b128 v[208:211], v193 offset:37888
	ds_read_b128 v[212:215], v193 offset:38912
	ds_read_b128 v[216:219], v193 offset:39936
	global_load_lds_dwordx4 v[226:227], off
	v_lshl_add_u64 v[226:227], s[30:31], 0, v[156:157]
	s_mov_b32 m0, s42
	s_nop 0
	global_load_lds_dwordx4 v[226:227], off
	s_waitcnt vmcnt(8)
	s_waitcnt lgkmcnt(0)
	s_barrier
	s_setprio 1
	s_waitcnt lgkmcnt(0)
	v_mfma_f32_16x16x32_bf16 v[124:127], v[128:131], v[176:179], v[124:127]
	v_mfma_f32_16x16x32_bf16 v[120:123], v[136:139], v[176:179], v[120:123]
	v_mfma_f32_16x16x32_bf16 v[108:111], v[128:131], v[196:199], v[108:111]
	v_mfma_f32_16x16x32_bf16 v[104:107], v[136:139], v[196:199], v[104:107]
	v_mfma_f32_16x16x32_bf16 v[92:95], v[128:131], v[204:207], v[92:95]
	v_mfma_f32_16x16x32_bf16 v[88:91], v[136:139], v[204:207], v[88:91]
	v_mfma_f32_16x16x32_bf16 v[76:79], v[128:131], v[212:215], v[76:79]
	v_mfma_f32_16x16x32_bf16 v[72:75], v[136:139], v[212:215], v[72:75]
	v_mfma_f32_16x16x32_bf16 v[124:127], v[132:135], v[180:183], v[124:127]
	v_mfma_f32_16x16x32_bf16 v[120:123], v[140:143], v[180:183], v[120:123]
	v_mfma_f32_16x16x32_bf16 v[108:111], v[132:135], v[200:203], v[108:111]
	v_mfma_f32_16x16x32_bf16 v[104:107], v[140:143], v[200:203], v[104:107]
	v_mfma_f32_16x16x32_bf16 v[92:95], v[132:135], v[208:211], v[92:95]
	v_mfma_f32_16x16x32_bf16 v[88:91], v[140:143], v[208:211], v[88:91]
	v_mfma_f32_16x16x32_bf16 v[76:79], v[132:135], v[216:219], v[76:79]
	v_mfma_f32_16x16x32_bf16 v[72:75], v[140:143], v[216:219], v[72:75]
	s_setprio 0
	s_setprio 1
	v_mfma_f32_16x16x32_bf16 v[116:119], v[144:147], v[176:179], v[116:119]
	v_mfma_f32_16x16x32_bf16 v[112:115], v[168:171], v[176:179], v[112:115]
	v_mfma_f32_16x16x32_bf16 v[100:103], v[144:147], v[196:199], v[100:103]
	v_mfma_f32_16x16x32_bf16 v[96:99], v[168:171], v[196:199], v[96:99]
	v_mfma_f32_16x16x32_bf16 v[84:87], v[144:147], v[204:207], v[84:87]
	v_mfma_f32_16x16x32_bf16 v[80:83], v[168:171], v[204:207], v[80:83]
	v_mfma_f32_16x16x32_bf16 v[68:71], v[144:147], v[212:215], v[68:71]
	v_mfma_f32_16x16x32_bf16 v[64:67], v[168:171], v[212:215], v[64:67]
	v_mfma_f32_16x16x32_bf16 v[116:119], v[148:151], v[180:183], v[116:119]
	v_mfma_f32_16x16x32_bf16 v[112:115], v[172:175], v[180:183], v[112:115]
	v_mfma_f32_16x16x32_bf16 v[100:103], v[148:151], v[200:203], v[100:103]
	v_mfma_f32_16x16x32_bf16 v[96:99], v[172:175], v[200:203], v[96:99]
	v_mfma_f32_16x16x32_bf16 v[84:87], v[148:151], v[208:211], v[84:87]
	v_mfma_f32_16x16x32_bf16 v[80:83], v[172:175], v[208:211], v[80:83]
	v_mfma_f32_16x16x32_bf16 v[68:71], v[148:151], v[216:219], v[68:71]
	v_mfma_f32_16x16x32_bf16 v[64:67], v[172:175], v[216:219], v[64:67]
	s_setprio 0
	s_barrier
; #define PG8_STAGE(bufoff, gbase, voff) do { _Pragma("unroll") for (int _i = 0; _i < 2; ++_i) \
;         __builtin_amdgcn_global_load_lds((const unsigned*)((const char*)(gbase) + (voff)[_i]), (LAS unsigned*)(lds + (bufoff) + ldsw + _i * 8192), 16, 0, 0); } while (0)
; #define PG8_LDA(dst, b, h) do { _Pragma("unroll") for (int m = 0; m < 4; ++m) _Pragma("unroll") for (int k = 0; k < 2; ++k) dst[m][k] = *(const LAS bf16x8*)(lds + PG8_SA(b, h) + aoff + m * 2048 + k * 1024); } while (0)
; #define PG8_MMA(ai, bj, At, Bt) do { __builtin_amdgcn_s_setprio(1); _Pragma("unroll") for (int m = 0; m < 4; ++m) _Pragma("unroll") for (int n = 0; n < 2; ++n) _Pragma("unroll") for (int k = 0; k < 2; ++k) \
;         acc[ai][bj][m][n] = __builtin_amdgcn_mfma_f32_16x16x32_bf16(Bt[n][k], At[m][k], acc[ai][bj][m][n], 0, 0, 0); __builtin_amdgcn_s_setprio(0); } while (0)
; #define PG8_WAIT_V(n) asm volatile("s_waitcnt vmcnt(" #n ")" ::: "memory")
; #define PG8_WAIT_L(n) asm volatile("s_waitcnt lgkmcnt(" #n ")" ::: "memory")
; #define PG8_BAR __builtin_amdgcn_s_barrier()
; #define PG8_SCHED __builtin_amdgcn_sched_barrier(0)
; template <class Epi, class Sched>
; __device__ __forceinline__ void gemm_phase(LAS unsigned char* lds, const Gemm g, const Sched& S, const Epi& E) {
;     ...
;         for (int t = 0; t < nt; t += 2) {
;             const bool last = (t == nt - 2);
;     ...
;             PG8_LDA(At, 1, 1); PG8_STAGE(PG8_SB(1, 0), b3, voffB); PG8_STAGE(PG8_SB(1, 1), b3 + hstepB, voffB); PG8_STAGE(PG8_SA(1, 0), a3, voffA);
;             PG8_WAIT_V(8); PG8_WAIT_L(0); PG8_BAR; PG8_MMA(1, 0, At, B0); PG8_MMA(1, 1, At, B1); PG8_BAR; PG8_SCHED;
	s_add_i32 s30, s56, s3
	v_lshl_add_u64 v[188:189], v[188:189], 0, s[16:17]
	s_mov_b32 m0, s30
	ds_read_b128 v[176:179], v193 offset:49152
	ds_read_b128 v[180:183], v193 offset:50176
	ds_read_b128 v[196:199], v193 offset:51200
	ds_read_b128 v[200:203], v193 offset:52224
	ds_read_b128 v[204:207], v193 offset:53248
	ds_read_b128 v[208:211], v193 offset:54272
	ds_read_b128 v[212:215], v193 offset:55296
	ds_read_b128 v[216:219], v193 offset:56320
	global_load_lds_dwordx4 v[188:189], off
	s_add_i32 m0, s30, 0x2000
	s_add_u32 s30, s36, 0x200080
	v_lshl_add_u64 v[188:189], v[220:221], 0, s[16:17]
	s_addc_u32 s31, s37, 0
	s_add_i32 s36, s57, s3
	global_load_lds_dwordx4 v[188:189], off
	v_lshl_add_u64 v[188:189], s[30:31], 0, v[154:155]
	s_mov_b32 m0, s36
	s_nop 0
	global_load_lds_dwordx4 v[188:189], off
	v_lshl_add_u64 v[188:189], s[30:31], 0, v[158:159]
	s_add_i32 m0, s36, 0x2000
	s_nop 0
	global_load_lds_dwordx4 v[188:189], off
	v_lshl_add_u64 v[188:189], v[222:223], 0, s[16:17]
	s_mov_b32 m0, s44
	s_nop 0
	global_load_lds_dwordx4 v[188:189], off
	v_lshl_add_u64 v[188:189], v[224:225], 0, s[16:17]
	s_mov_b32 m0, s45
	s_nop 0
	global_load_lds_dwordx4 v[188:189], off
	s_waitcnt vmcnt(8)
	s_waitcnt lgkmcnt(0)
	s_barrier
	s_setprio 1
	s_waitcnt lgkmcnt(0)
	v_mfma_f32_16x16x32_bf16 v[60:63], v[128:131], v[176:179], v[60:63]
	v_mfma_f32_16x16x32_bf16 v[56:59], v[136:139], v[176:179], v[56:59]
	s_add_i32 s55, s55, 2
	v_mfma_f32_16x16x32_bf16 v[44:47], v[128:131], v[196:199], v[44:47]
	s_add_u32 s53, s53, 0x100
	v_mfma_f32_16x16x32_bf16 v[40:43], v[136:139], v[196:199], v[40:43]
	s_addc_u32 s54, s54, 0
	v_mfma_f32_16x16x32_bf16 v[28:31], v[128:131], v[204:207], v[28:31]
	s_mov_b64 s[30:31], s[34:35]
	v_mfma_f32_16x16x32_bf16 v[24:27], v[136:139], v[204:207], v[24:27]
	s_cmpk_gt_u32 s55, 0x7d
	v_mfma_f32_16x16x32_bf16 v[12:15], v[128:131], v[212:215], v[12:15]
	v_mfma_f32_16x16x32_bf16 v[8:11], v[136:139], v[212:215], v[8:11]
	v_mfma_f32_16x16x32_bf16 v[60:63], v[132:135], v[180:183], v[60:63]
	v_mfma_f32_16x16x32_bf16 v[56:59], v[140:143], v[180:183], v[56:59]
	v_mfma_f32_16x16x32_bf16 v[44:47], v[132:135], v[200:203], v[44:47]
	v_mfma_f32_16x16x32_bf16 v[40:43], v[140:143], v[200:203], v[40:43]
	v_mfma_f32_16x16x32_bf16 v[28:31], v[132:135], v[208:211], v[28:31]
	v_mfma_f32_16x16x32_bf16 v[24:27], v[140:143], v[208:211], v[24:27]
	v_mfma_f32_16x16x32_bf16 v[12:15], v[132:135], v[216:219], v[12:15]
	v_mfma_f32_16x16x32_bf16 v[8:11], v[140:143], v[216:219], v[8:11]
	s_setprio 0
	s_setprio 1
	v_mfma_f32_16x16x32_bf16 v[52:55], v[144:147], v[176:179], v[52:55]
	v_mfma_f32_16x16x32_bf16 v[48:51], v[168:171], v[176:179], v[48:51]
	v_mfma_f32_16x16x32_bf16 v[36:39], v[144:147], v[196:199], v[36:39]
	v_mfma_f32_16x16x32_bf16 v[32:35], v[168:171], v[196:199], v[32:35]
	v_mfma_f32_16x16x32_bf16 v[20:23], v[144:147], v[204:207], v[20:23]
	v_mfma_f32_16x16x32_bf16 v[16:19], v[168:171], v[204:207], v[16:19]
	v_mfma_f32_16x16x32_bf16 v[4:7], v[144:147], v[212:215], v[4:7]
	v_mfma_f32_16x16x32_bf16 v[0:3], v[168:171], v[212:215], v[0:3]
	v_mfma_f32_16x16x32_bf16 v[52:55], v[148:151], v[180:183], v[52:55]
	v_mfma_f32_16x16x32_bf16 v[48:51], v[172:175], v[180:183], v[48:51]
	v_mfma_f32_16x16x32_bf16 v[36:39], v[148:151], v[200:203], v[36:39]
	v_mfma_f32_16x16x32_bf16 v[32:35], v[172:175], v[200:203], v[32:35]
	v_mfma_f32_16x16x32_bf16 v[20:23], v[148:151], v[208:211], v[20:23]
	v_mfma_f32_16x16x32_bf16 v[16:19], v[172:175], v[208:211], v[16:19]
	v_mfma_f32_16x16x32_bf16 v[4:7], v[148:151], v[216:219], v[4:7]
	v_mfma_f32_16x16x32_bf16 v[0:3], v[172:175], v[216:219], v[0:3]
	s_setprio 0
	s_barrier
	s_cbranch_scc0 .LBB0_1028
	s_and_b64 vcc, exec, s[18:19]
	s_cbranch_vccz .LBB0_1031
	s_barrier
